# st2 epilogue: bf16 rows loaded with global_load_short_d16_hi into pre-zeroed regs (no shifts), conv packed per batch pair
# baseline (speedup 1.0000x reference)
; HD float2 cmul(float2 a, float2 b){ return make_float2(a.x*b.x - a.y*b.y, a.x*b.y + a.y*b.x); }
; HD float2 cmulc(float2 a, float2 b){ return make_float2(a.x*b.x + a.y*b.y, a.y*b.x - a.x*b.y); }
; template<bool INV, bool NOTW>
; HD void bf4c(float2* Z, int i0, int i1, int i2, int i3, float2 w1, float2 w2, float2 w3){
;   float2 a0=Z[i0], a1=Z[i1], a2=Z[i2], a3=Z[i3];
;   if (INV && !NOTW){ a1=cmulc(a1,w1); a2=cmulc(a2,w2); a3=cmulc(a3,w3); }
;   float2 s02=make_float2(a0.x+a2.x,a0.y+a2.y), d02=make_float2(a0.x-a2.x,a0.y-a2.y);
;   float2 s13=make_float2(a1.x+a3.x,a1.y+a3.y), d13=make_float2(a1.x-a3.x,a1.y-a3.y);
;   float2 y0=make_float2(s02.x+s13.x,s02.y+s13.y), y2=make_float2(s02.x-s13.x,s02.y-s13.y);
;   float2 ym=make_float2(d02.x+d13.y,d02.y-d13.x);
;   float2 yp=make_float2(d02.x-d13.y,d02.y+d13.x);
;   float2 y1, y3;
;   if (INV){ y1=yp; y3=ym; } else if (NOTW){ y1=ym; y3=yp; } else { y1=cmul(ym,w1); y2=cmul(y2,w2); y3=cmul(yp,w3); }
;   Z[i0]=y0; Z[i1]=y1; Z[i2]=y2; Z[i3]=y3;
; }
; template<bool INV, int LQ, bool BARRIER=true>
; HD void fft_pass(float2* Z, const float2* twA, const float2* twB, int tid){
;     ...
;   } else {
;     int j=tid&(q-1); int base0=((tid>>LQ)<<(LQ+2))+j;
;     float2 w1=make_float2(1.f,0.f), w2=w1, w3=w1;
;     if (LQ>0){ int k=j*tws; w1=cmul(twA[k>>6],twB[k&63]); w2=cmul(w1,w1); w3=cmul(w2,w1); }
;     _Pragma("unroll") for (int i=0;i<8;++i){ int base=base0+i*2048; bf4c<INV,(LQ==0)>(Z,base,base+q,base+2*q,base+3*q,w1,w2,w3); }
;   }
;   if (BARRIER) __syncthreads(); else asm volatile("s_waitcnt lgkmcnt(0)" ::: "memory");
; }
; __device__ __forceinline__ void fft_fwd_head(float2* Z, const float2* twA, const float2* twB, int tid){
;   fft_pass<false,10>(Z,twA,twB,tid); fft_pass<false,8>(Z,twA,twB,tid); fft_pass<false,6,false>(Z,twA,twB,tid);
;   fft_pass<false,4,false>(Z,twA,twB,tid); fft_pass<false,2,false>(Z,twA,twB,tid);
; }
; __device__ __forceinline__ void fft_inv_tail(float2* Z, const float2* twA, const float2* twB, int tid){
;   fft_pass<true,2,false>(Z,twA,twB,tid); fft_pass<true,4,false>(Z,twA,twB,tid); fft_pass<true,6>(Z,twA,twB,tid);
;   fft_pass<true,8>(Z,twA,twB,tid); fft_pass<true,10>(Z,twA,twB,tid);
; }
.Lmy_pf_st1:
	s_add_u32 s98, s98, 0x1000000
	s_addc_u32 s99, s99, 0
	global_load_dwordx4 v[228:231], v232, s[98:99]
	global_load_dwordx4 v[228:231], v233, s[98:99]
	global_load_dwordx4 v[228:231], v234, s[98:99]
	global_load_dwordx4 v[228:231], v235, s[98:99]
	s_waitcnt lgkmcnt(0)
	v_mov_b32_e32 v222, 0x3f6c835e
	v_mov_b32_e32 v223, 0x3ec3ef15
	v_mov_b32_e32 v224, 0x3f3504f3
	v_mov_b32_e32 v225, 0x3f3504f3
	v_and_b32_e32 v8, 15, v154
	v_lshlrev_b32_e32 v9, 3, v8
	v_add_u32_e32 v9, 0x20800, v9
	v_mov_b32_e32 v10, 0x20a00
	ds_read_b64 v[0:1], v9
	ds_read_b64 v[2:3], v10
	s_waitcnt lgkmcnt(0)
	v_pk_mul_f32 v[250:251], v[0:1], v[2:3] op_sel:[1,1] op_sel_hi:[1,0]
	v_pk_fma_f32 v[80:81], v[0:1], v[2:3], v[250:251] op_sel:[0,0,0] op_sel_hi:[0,1,1] neg_lo:[0,0,1]
	v_pk_mul_f32 v[250:251], v[80:81], v[80:81] op_sel:[1,1] op_sel_hi:[1,0]
	v_pk_fma_f32 v[82:83], v[80:81], v[80:81], v[250:251] op_sel:[0,0,0] op_sel_hi:[0,1,1] neg_lo:[0,0,1]
	v_pk_mul_f32 v[250:251], v[82:83], v[80:81] op_sel:[1,1] op_sel_hi:[1,0]
	v_pk_fma_f32 v[84:85], v[82:83], v[80:81], v[250:251] op_sel:[0,0,0] op_sel_hi:[0,1,1] neg_lo:[0,0,1]
	v_lshlrev_b32_e32 v9, 5, v8
	v_add_u32_e32 v9, 0x20800, v9
	v_mov_b32_e32 v10, 0x20a00
	ds_read_b64 v[0:1], v9
	ds_read_b64 v[2:3], v10
	s_waitcnt lgkmcnt(0)
	v_pk_mul_f32 v[250:251], v[0:1], v[2:3] op_sel:[1,1] op_sel_hi:[1,0]
	v_pk_fma_f32 v[236:237], v[0:1], v[2:3], v[250:251] op_sel:[0,0,0] op_sel_hi:[0,1,1] neg_lo:[0,0,1]
	v_pk_mul_f32 v[250:251], v[236:237], v[236:237] op_sel:[1,1] op_sel_hi:[1,0]
	v_pk_fma_f32 v[238:239], v[236:237], v[236:237], v[250:251] op_sel:[0,0,0] op_sel_hi:[0,1,1] neg_lo:[0,0,1]
	v_pk_mul_f32 v[250:251], v[238:239], v[236:237] op_sel:[1,1] op_sel_hi:[1,0]
	v_pk_fma_f32 v[240:241], v[238:239], v[236:237], v[250:251] op_sel:[0,0,0] op_sel_hi:[0,1,1] neg_lo:[0,0,1]
	v_lshrrev_b32_e32 v226, 6, v154
	v_bfe_u32 v227, v154, 4, 2
	v_lshl_add_u32 v226, v227, 3, v226
	v_lshlrev_b32_e32 v226, 8, v226
	v_and_b32_e32 v227, 15, v154
	v_add_u32_e32 v226, v226, v227
	v_lshlrev_b32_e32 v226, 3, v226
	v_add_u32_e32 v227, 0x10000, v226
	ds_read_b64 v[0:1], v226 offset:0
	ds_read_b64 v[2:3], v226 offset:128
	ds_read_b64 v[4:5], v226 offset:256
	ds_read_b64 v[6:7], v226 offset:384
	ds_read_b64 v[8:9], v226 offset:512
	ds_read_b64 v[10:11], v226 offset:640
	ds_read_b64 v[12:13], v226 offset:768
	ds_read_b64 v[14:15], v226 offset:896
	ds_read_b64 v[16:17], v226 offset:1024
	ds_read_b64 v[18:19], v226 offset:1152
	ds_read_b64 v[20:21], v226 offset:1280
	ds_read_b64 v[22:23], v226 offset:1408
	ds_read_b64 v[24:25], v226 offset:1536
	ds_read_b64 v[26:27], v226 offset:1664
	ds_read_b64 v[28:29], v226 offset:1792
	ds_read_b64 v[30:31], v226 offset:1920
	s_waitcnt lgkmcnt(12)
	v_pk_mul_f32 v[250:251], v[4:5], v[238:239] op_sel:[1,1] op_sel_hi:[0,1]
	v_pk_fma_f32 v[4:5], v[4:5], v[238:239], v[250:251] op_sel:[0,0,0] op_sel_hi:[1,0,1] neg_hi:[0,0,1]
	v_pk_mul_f32 v[250:251], v[2:3], v[236:237] op_sel:[1,1] op_sel_hi:[0,1]
	v_pk_fma_f32 v[2:3], v[2:3], v[236:237], v[250:251] op_sel:[0,0,0] op_sel_hi:[1,0,1] neg_hi:[0,0,1]
	v_pk_mul_f32 v[250:251], v[6:7], v[240:241] op_sel:[1,1] op_sel_hi:[0,1]
	v_pk_fma_f32 v[6:7], v[6:7], v[240:241], v[250:251] op_sel:[0,0,0] op_sel_hi:[1,0,1] neg_hi:[0,0,1]
	v_pk_add_f32 v[242:243], v[0:1], v[4:5]
	v_pk_add_f32 v[244:245], v[0:1], v[4:5] neg_lo:[0,1] neg_hi:[0,1]
	v_pk_add_f32 v[246:247], v[2:3], v[6:7]
	v_pk_add_f32 v[248:249], v[2:3], v[6:7] neg_lo:[0,1] neg_hi:[0,1]
	v_pk_add_f32 v[0:1], v[242:243], v[246:247]
	v_pk_add_f32 v[2:3], v[244:245], v[248:249] op_sel:[0,1] op_sel_hi:[1,0] neg_lo:[0,1]
	v_pk_add_f32 v[4:5], v[242:243], v[246:247] neg_lo:[0,1] neg_hi:[0,1]
	v_pk_add_f32 v[6:7], v[244:245], v[248:249] op_sel:[0,1] op_sel_hi:[1,0] neg_hi:[0,1]
	s_waitcnt lgkmcnt(8)
	v_pk_mul_f32 v[250:251], v[12:13], v[238:239] op_sel:[1,1] op_sel_hi:[0,1]
	v_pk_fma_f32 v[12:13], v[12:13], v[238:239], v[250:251] op_sel:[0,0,0] op_sel_hi:[1,0,1] neg_hi:[0,0,1]
	v_pk_mul_f32 v[250:251], v[10:11], v[236:237] op_sel:[1,1] op_sel_hi:[0,1]
	v_pk_fma_f32 v[10:11], v[10:11], v[236:237], v[250:251] op_sel:[0,0,0] op_sel_hi:[1,0,1] neg_hi:[0,0,1]
	v_pk_mul_f32 v[250:251], v[14:15], v[240:241] op_sel:[1,1] op_sel_hi:[0,1]
	v_pk_fma_f32 v[14:15], v[14:15], v[240:241], v[250:251] op_sel:[0,0,0] op_sel_hi:[1,0,1] neg_hi:[0,0,1]
	v_pk_add_f32 v[242:243], v[8:9], v[12:13]
	v_pk_add_f32 v[244:245], v[8:9], v[12:13] neg_lo:[0,1] neg_hi:[0,1]
	v_pk_add_f32 v[246:247], v[10:11], v[14:15]
	v_pk_add_f32 v[248:249], v[10:11], v[14:15] neg_lo:[0,1] neg_hi:[0,1]
	v_pk_add_f32 v[8:9], v[242:243], v[246:247]
	v_pk_add_f32 v[10:11], v[244:245], v[248:249] op_sel:[0,1] op_sel_hi:[1,0] neg_lo:[0,1]
	v_pk_add_f32 v[12:13], v[242:243], v[246:247] neg_lo:[0,1] neg_hi:[0,1]
	v_pk_add_f32 v[14:15], v[244:245], v[248:249] op_sel:[0,1] op_sel_hi:[1,0] neg_hi:[0,1]
	s_waitcnt lgkmcnt(4)
	v_pk_mul_f32 v[250:251], v[20:21], v[238:239] op_sel:[1,1] op_sel_hi:[0,1]
	v_pk_fma_f32 v[20:21], v[20:21], v[238:239], v[250:251] op_sel:[0,0,0] op_sel_hi:[1,0,1] neg_hi:[0,0,1]
	v_pk_mul_f32 v[250:251], v[18:19], v[236:237] op_sel:[1,1] op_sel_hi:[0,1]
	v_pk_fma_f32 v[18:19], v[18:19], v[236:237], v[250:251] op_sel:[0,0,0] op_sel_hi:[1,0,1] neg_hi:[0,0,1]
	v_pk_mul_f32 v[250:251], v[22:23], v[240:241] op_sel:[1,1] op_sel_hi:[0,1]
	v_pk_fma_f32 v[22:23], v[22:23], v[240:241], v[250:251] op_sel:[0,0,0] op_sel_hi:[1,0,1] neg_hi:[0,0,1]
	v_pk_add_f32 v[242:243], v[16:17], v[20:21]
	v_pk_add_f32 v[244:245], v[16:17], v[20:21] neg_lo:[0,1] neg_hi:[0,1]
	v_pk_add_f32 v[246:247], v[18:19], v[22:23]
	v_pk_add_f32 v[248:249], v[18:19], v[22:23] neg_lo:[0,1] neg_hi:[0,1]
	v_pk_add_f32 v[16:17], v[242:243], v[246:247]
	v_pk_add_f32 v[18:19], v[244:245], v[248:249] op_sel:[0,1] op_sel_hi:[1,0] neg_lo:[0,1]
	v_pk_add_f32 v[20:21], v[242:243], v[246:247] neg_lo:[0,1] neg_hi:[0,1]
	v_pk_add_f32 v[22:23], v[244:245], v[248:249] op_sel:[0,1] op_sel_hi:[1,0] neg_hi:[0,1]
	s_waitcnt lgkmcnt(0)
; HD float2 cmul(float2 a, float2 b){ return make_float2(a.x*b.x - a.y*b.y, a.x*b.y + a.y*b.x); }
; HD float2 cmulc(float2 a, float2 b){ return make_float2(a.x*b.x + a.y*b.y, a.y*b.x - a.x*b.y); }
; template<bool INV, bool NOTW>
; HD void bf4c(float2* Z, int i0, int i1, int i2, int i3, float2 w1, float2 w2, float2 w3){
;   float2 a0=Z[i0], a1=Z[i1], a2=Z[i2], a3=Z[i3];
;   if (INV && !NOTW){ a1=cmulc(a1,w1); a2=cmulc(a2,w2); a3=cmulc(a3,w3); }
;   float2 s02=make_float2(a0.x+a2.x,a0.y+a2.y), d02=make_float2(a0.x-a2.x,a0.y-a2.y);
;   float2 s13=make_float2(a1.x+a3.x,a1.y+a3.y), d13=make_float2(a1.x-a3.x,a1.y-a3.y);
;   float2 y0=make_float2(s02.x+s13.x,s02.y+s13.y), y2=make_float2(s02.x-s13.x,s02.y-s13.y);
;   float2 ym=make_float2(d02.x+d13.y,d02.y-d13.x);
;   float2 yp=make_float2(d02.x-d13.y,d02.y+d13.x);
;   float2 y1, y3;
;   if (INV){ y1=yp; y3=ym; } else if (NOTW){ y1=ym; y3=yp; } else { y1=cmul(ym,w1); y2=cmul(y2,w2); y3=cmul(yp,w3); }
;   Z[i0]=y0; Z[i1]=y1; Z[i2]=y2; Z[i3]=y3;
; }
; template<bool INV, int LQ, bool BARRIER=true>
; HD void fft_pass(float2* Z, const float2* twA, const float2* twB, int tid){
;     ...
;   } else {
;     int j=tid&(q-1); int base0=((tid>>LQ)<<(LQ+2))+j;
;     float2 w1=make_float2(1.f,0.f), w2=w1, w3=w1;
;     if (LQ>0){ int k=j*tws; w1=cmul(twA[k>>6],twB[k&63]); w2=cmul(w1,w1); w3=cmul(w2,w1); }
;     _Pragma("unroll") for (int i=0;i<8;++i){ int base=base0+i*2048; bf4c<INV,(LQ==0)>(Z,base,base+q,base+2*q,base+3*q,w1,w2,w3); }
;   }
;   if (BARRIER) __syncthreads(); else asm volatile("s_waitcnt lgkmcnt(0)" ::: "memory");
; }
; __device__ __forceinline__ void fft_fwd_head(float2* Z, const float2* twA, const float2* twB, int tid){
;   fft_pass<false,10>(Z,twA,twB,tid); fft_pass<false,8>(Z,twA,twB,tid); fft_pass<false,6,false>(Z,twA,twB,tid);
;   fft_pass<false,4,false>(Z,twA,twB,tid); fft_pass<false,2,false>(Z,twA,twB,tid);
; }
; __device__ __forceinline__ void fft_inv_tail(float2* Z, const float2* twA, const float2* twB, int tid){
;   fft_pass<true,2,false>(Z,twA,twB,tid); fft_pass<true,4,false>(Z,twA,twB,tid); fft_pass<true,6>(Z,twA,twB,tid);
;   fft_pass<true,8>(Z,twA,twB,tid); fft_pass<true,10>(Z,twA,twB,tid);
; }
	v_pk_mul_f32 v[250:251], v[28:29], v[238:239] op_sel:[1,1] op_sel_hi:[0,1]
	v_pk_fma_f32 v[28:29], v[28:29], v[238:239], v[250:251] op_sel:[0,0,0] op_sel_hi:[1,0,1] neg_hi:[0,0,1]
	v_pk_mul_f32 v[250:251], v[26:27], v[236:237] op_sel:[1,1] op_sel_hi:[0,1]
	v_pk_fma_f32 v[26:27], v[26:27], v[236:237], v[250:251] op_sel:[0,0,0] op_sel_hi:[1,0,1] neg_hi:[0,0,1]
	v_pk_mul_f32 v[250:251], v[30:31], v[240:241] op_sel:[1,1] op_sel_hi:[0,1]
	v_pk_fma_f32 v[30:31], v[30:31], v[240:241], v[250:251] op_sel:[0,0,0] op_sel_hi:[1,0,1] neg_hi:[0,0,1]
	v_pk_add_f32 v[242:243], v[24:25], v[28:29]
	v_pk_add_f32 v[244:245], v[24:25], v[28:29] neg_lo:[0,1] neg_hi:[0,1]
	v_pk_add_f32 v[246:247], v[26:27], v[30:31]
	v_pk_add_f32 v[248:249], v[26:27], v[30:31] neg_lo:[0,1] neg_hi:[0,1]
	v_pk_add_f32 v[24:25], v[242:243], v[246:247]
	v_pk_add_f32 v[26:27], v[244:245], v[248:249] op_sel:[0,1] op_sel_hi:[1,0] neg_lo:[0,1]
	v_pk_add_f32 v[28:29], v[242:243], v[246:247] neg_lo:[0,1] neg_hi:[0,1]
	v_pk_add_f32 v[30:31], v[244:245], v[248:249] op_sel:[0,1] op_sel_hi:[1,0] neg_hi:[0,1]
	v_pk_mul_f32 v[250:251], v[16:17], v[82:83] op_sel:[1,1] op_sel_hi:[0,1]
	v_pk_fma_f32 v[16:17], v[16:17], v[82:83], v[250:251] op_sel:[0,0,0] op_sel_hi:[1,0,1] neg_hi:[0,0,1]
	v_pk_mul_f32 v[250:251], v[8:9], v[80:81] op_sel:[1,1] op_sel_hi:[0,1]
	v_pk_fma_f32 v[8:9], v[8:9], v[80:81], v[250:251] op_sel:[0,0,0] op_sel_hi:[1,0,1] neg_hi:[0,0,1]
	v_pk_mul_f32 v[250:251], v[24:25], v[84:85] op_sel:[1,1] op_sel_hi:[0,1]
	v_pk_fma_f32 v[24:25], v[24:25], v[84:85], v[250:251] op_sel:[0,0,0] op_sel_hi:[1,0,1] neg_hi:[0,0,1]
	v_pk_add_f32 v[242:243], v[0:1], v[16:17]
	v_pk_add_f32 v[244:245], v[0:1], v[16:17] neg_lo:[0,1] neg_hi:[0,1]
	v_pk_add_f32 v[246:247], v[8:9], v[24:25]
	v_pk_add_f32 v[248:249], v[8:9], v[24:25] neg_lo:[0,1] neg_hi:[0,1]
	v_pk_add_f32 v[0:1], v[242:243], v[246:247]
	ds_write_b64 v226, v[0:1] offset:0
	v_pk_add_f32 v[8:9], v[244:245], v[248:249] op_sel:[0,1] op_sel_hi:[1,0] neg_lo:[0,1]
	ds_write_b64 v226, v[8:9] offset:512
	v_pk_add_f32 v[16:17], v[242:243], v[246:247] neg_lo:[0,1] neg_hi:[0,1]
	ds_write_b64 v226, v[16:17] offset:1024
	v_pk_add_f32 v[24:25], v[244:245], v[248:249] op_sel:[0,1] op_sel_hi:[1,0] neg_hi:[0,1]
	ds_write_b64 v226, v[24:25] offset:1536
	v_pk_mul_f32 v[250:251], v[18:19], v[224:225] op_sel:[1,1] op_sel_hi:[1,0] neg_lo:[0,0] neg_hi:[0,0]
	v_pk_fma_f32 v[18:19], v[18:19], v[224:225], v[250:251] op_sel:[0,0,0] op_sel_hi:[0,1,1] neg_lo:[0,0,1] neg_hi:[0,0,0]
	v_pk_mul_f32 v[250:251], v[18:19], v[82:83] op_sel:[1,1] op_sel_hi:[0,1]
	v_pk_fma_f32 v[18:19], v[18:19], v[82:83], v[250:251] op_sel:[0,0,0] op_sel_hi:[1,0,1] neg_hi:[0,0,1]
	v_pk_mul_f32 v[250:251], v[10:11], v[222:223] op_sel:[1,1] op_sel_hi:[1,0] neg_lo:[0,0] neg_hi:[0,0]
	v_pk_fma_f32 v[10:11], v[10:11], v[222:223], v[250:251] op_sel:[0,0,0] op_sel_hi:[0,1,1] neg_lo:[0,0,1] neg_hi:[0,0,0]
	v_pk_mul_f32 v[250:251], v[10:11], v[80:81] op_sel:[1,1] op_sel_hi:[0,1]
	v_pk_fma_f32 v[10:11], v[10:11], v[80:81], v[250:251] op_sel:[0,0,0] op_sel_hi:[1,0,1] neg_hi:[0,0,1]
	v_pk_mul_f32 v[250:251], v[26:27], v[222:223] op_sel:[1,0] op_sel_hi:[1,1] neg_lo:[0,0] neg_hi:[0,0]
	v_pk_fma_f32 v[26:27], v[26:27], v[222:223], v[250:251] op_sel:[0,1,0] op_sel_hi:[0,0,1] neg_lo:[0,0,1] neg_hi:[0,0,0]
	v_pk_mul_f32 v[250:251], v[26:27], v[84:85] op_sel:[1,1] op_sel_hi:[0,1]
	v_pk_fma_f32 v[26:27], v[26:27], v[84:85], v[250:251] op_sel:[0,0,0] op_sel_hi:[1,0,1] neg_hi:[0,0,1]
	v_pk_add_f32 v[242:243], v[2:3], v[18:19]
	v_pk_add_f32 v[244:245], v[2:3], v[18:19] neg_lo:[0,1] neg_hi:[0,1]
	v_pk_add_f32 v[246:247], v[10:11], v[26:27]
	v_pk_add_f32 v[248:249], v[10:11], v[26:27] neg_lo:[0,1] neg_hi:[0,1]
	v_pk_add_f32 v[2:3], v[242:243], v[246:247]
	ds_write_b64 v226, v[2:3] offset:128
	v_pk_add_f32 v[10:11], v[244:245], v[248:249] op_sel:[0,1] op_sel_hi:[1,0] neg_lo:[0,1]
	ds_write_b64 v226, v[10:11] offset:640
	v_pk_add_f32 v[18:19], v[242:243], v[246:247] neg_lo:[0,1] neg_hi:[0,1]
	ds_write_b64 v226, v[18:19] offset:1152
	v_pk_add_f32 v[26:27], v[244:245], v[248:249] op_sel:[0,1] op_sel_hi:[1,0] neg_hi:[0,1]
	ds_write_b64 v226, v[26:27] offset:1664
	v_pk_add_f32 v[20:21], v[20:21], 0 op_sel:[1,0] op_sel_hi:[0,0] neg_lo:[1,0]
	v_pk_mul_f32 v[250:251], v[20:21], v[82:83] op_sel:[1,1] op_sel_hi:[0,1]
	v_pk_fma_f32 v[20:21], v[20:21], v[82:83], v[250:251] op_sel:[0,0,0] op_sel_hi:[1,0,1] neg_hi:[0,0,1]
	v_pk_mul_f32 v[250:251], v[12:13], v[224:225] op_sel:[1,1] op_sel_hi:[1,0] neg_lo:[0,0] neg_hi:[0,0]
	v_pk_fma_f32 v[12:13], v[12:13], v[224:225], v[250:251] op_sel:[0,0,0] op_sel_hi:[0,1,1] neg_lo:[0,0,1] neg_hi:[0,0,0]
	v_pk_mul_f32 v[250:251], v[12:13], v[80:81] op_sel:[1,1] op_sel_hi:[0,1]
	v_pk_fma_f32 v[12:13], v[12:13], v[80:81], v[250:251] op_sel:[0,0,0] op_sel_hi:[1,0,1] neg_hi:[0,0,1]
	v_pk_mul_f32 v[250:251], v[28:29], v[224:225] op_sel:[1,1] op_sel_hi:[1,0] neg_lo:[0,0] neg_hi:[0,1]
	v_pk_fma_f32 v[28:29], v[28:29], v[224:225], v[250:251] op_sel:[0,0,0] op_sel_hi:[0,1,1] neg_lo:[0,1,1] neg_hi:[0,0,0]
	v_pk_mul_f32 v[250:251], v[28:29], v[84:85] op_sel:[1,1] op_sel_hi:[0,1]
	v_pk_fma_f32 v[28:29], v[28:29], v[84:85], v[250:251] op_sel:[0,0,0] op_sel_hi:[1,0,1] neg_hi:[0,0,1]
	v_pk_add_f32 v[242:243], v[4:5], v[20:21]
	v_pk_add_f32 v[244:245], v[4:5], v[20:21] neg_lo:[0,1] neg_hi:[0,1]
	v_pk_add_f32 v[246:247], v[12:13], v[28:29]
	v_pk_add_f32 v[248:249], v[12:13], v[28:29] neg_lo:[0,1] neg_hi:[0,1]
	v_pk_add_f32 v[4:5], v[242:243], v[246:247]
	ds_write_b64 v226, v[4:5] offset:256
	v_pk_add_f32 v[12:13], v[244:245], v[248:249] op_sel:[0,1] op_sel_hi:[1,0] neg_lo:[0,1]
	ds_write_b64 v226, v[12:13] offset:768
; HD float2 cmul(float2 a, float2 b){ return make_float2(a.x*b.x - a.y*b.y, a.x*b.y + a.y*b.x); }
; HD float2 cmulc(float2 a, float2 b){ return make_float2(a.x*b.x + a.y*b.y, a.y*b.x - a.x*b.y); }
; template<bool INV, bool NOTW>
; HD void bf4c(float2* Z, int i0, int i1, int i2, int i3, float2 w1, float2 w2, float2 w3){
;   float2 a0=Z[i0], a1=Z[i1], a2=Z[i2], a3=Z[i3];
;   if (INV && !NOTW){ a1=cmulc(a1,w1); a2=cmulc(a2,w2); a3=cmulc(a3,w3); }
;   float2 s02=make_float2(a0.x+a2.x,a0.y+a2.y), d02=make_float2(a0.x-a2.x,a0.y-a2.y);
;   float2 s13=make_float2(a1.x+a3.x,a1.y+a3.y), d13=make_float2(a1.x-a3.x,a1.y-a3.y);
;   float2 y0=make_float2(s02.x+s13.x,s02.y+s13.y), y2=make_float2(s02.x-s13.x,s02.y-s13.y);
;   float2 ym=make_float2(d02.x+d13.y,d02.y-d13.x);
;   float2 yp=make_float2(d02.x-d13.y,d02.y+d13.x);
;   float2 y1, y3;
;   if (INV){ y1=yp; y3=ym; } else if (NOTW){ y1=ym; y3=yp; } else { y1=cmul(ym,w1); y2=cmul(y2,w2); y3=cmul(yp,w3); }
;   Z[i0]=y0; Z[i1]=y1; Z[i2]=y2; Z[i3]=y3;
; }
; template<bool INV, int LQ, bool BARRIER=true>
; HD void fft_pass(float2* Z, const float2* twA, const float2* twB, int tid){
;     ...
;   } else {
;     int j=tid&(q-1); int base0=((tid>>LQ)<<(LQ+2))+j;
;     float2 w1=make_float2(1.f,0.f), w2=w1, w3=w1;
;     if (LQ>0){ int k=j*tws; w1=cmul(twA[k>>6],twB[k&63]); w2=cmul(w1,w1); w3=cmul(w2,w1); }
;     _Pragma("unroll") for (int i=0;i<8;++i){ int base=base0+i*2048; bf4c<INV,(LQ==0)>(Z,base,base+q,base+2*q,base+3*q,w1,w2,w3); }
;   }
;   if (BARRIER) __syncthreads(); else asm volatile("s_waitcnt lgkmcnt(0)" ::: "memory");
; }
; __device__ __forceinline__ void fft_fwd_head(float2* Z, const float2* twA, const float2* twB, int tid){
;   fft_pass<false,10>(Z,twA,twB,tid); fft_pass<false,8>(Z,twA,twB,tid); fft_pass<false,6,false>(Z,twA,twB,tid);
;   fft_pass<false,4,false>(Z,twA,twB,tid); fft_pass<false,2,false>(Z,twA,twB,tid);
; }
; __device__ __forceinline__ void fft_inv_tail(float2* Z, const float2* twA, const float2* twB, int tid){
;   fft_pass<true,2,false>(Z,twA,twB,tid); fft_pass<true,4,false>(Z,twA,twB,tid); fft_pass<true,6>(Z,twA,twB,tid);
;   fft_pass<true,8>(Z,twA,twB,tid); fft_pass<true,10>(Z,twA,twB,tid);
; }
	v_pk_add_f32 v[20:21], v[242:243], v[246:247] neg_lo:[0,1] neg_hi:[0,1]
	ds_write_b64 v226, v[20:21] offset:1280
	v_pk_add_f32 v[28:29], v[244:245], v[248:249] op_sel:[0,1] op_sel_hi:[1,0] neg_hi:[0,1]
	ds_write_b64 v226, v[28:29] offset:1792
	v_pk_mul_f32 v[250:251], v[22:23], v[224:225] op_sel:[1,1] op_sel_hi:[1,0] neg_lo:[0,0] neg_hi:[0,1]
	v_pk_fma_f32 v[22:23], v[22:23], v[224:225], v[250:251] op_sel:[0,0,0] op_sel_hi:[0,1,1] neg_lo:[0,1,1] neg_hi:[0,0,0]
	v_pk_mul_f32 v[250:251], v[22:23], v[82:83] op_sel:[1,1] op_sel_hi:[0,1]
	v_pk_fma_f32 v[22:23], v[22:23], v[82:83], v[250:251] op_sel:[0,0,0] op_sel_hi:[1,0,1] neg_hi:[0,0,1]
	v_pk_mul_f32 v[250:251], v[14:15], v[222:223] op_sel:[1,0] op_sel_hi:[1,1] neg_lo:[0,0] neg_hi:[0,0]
	v_pk_fma_f32 v[14:15], v[14:15], v[222:223], v[250:251] op_sel:[0,1,0] op_sel_hi:[0,0,1] neg_lo:[0,0,1] neg_hi:[0,0,0]
	v_pk_mul_f32 v[250:251], v[14:15], v[80:81] op_sel:[1,1] op_sel_hi:[0,1]
	v_pk_fma_f32 v[14:15], v[14:15], v[80:81], v[250:251] op_sel:[0,0,0] op_sel_hi:[1,0,1] neg_hi:[0,0,1]
	v_pk_mul_f32 v[250:251], v[30:31], v[222:223] op_sel:[1,1] op_sel_hi:[1,0] neg_lo:[0,1] neg_hi:[0,1]
	v_pk_fma_f32 v[30:31], v[30:31], v[222:223], v[250:251] op_sel:[0,0,0] op_sel_hi:[0,1,1] neg_lo:[0,1,1] neg_hi:[0,1,0]
	v_pk_mul_f32 v[250:251], v[30:31], v[84:85] op_sel:[1,1] op_sel_hi:[0,1]
	v_pk_fma_f32 v[30:31], v[30:31], v[84:85], v[250:251] op_sel:[0,0,0] op_sel_hi:[1,0,1] neg_hi:[0,0,1]
	v_pk_add_f32 v[242:243], v[6:7], v[22:23]
	v_pk_add_f32 v[244:245], v[6:7], v[22:23] neg_lo:[0,1] neg_hi:[0,1]
	v_pk_add_f32 v[246:247], v[14:15], v[30:31]
	v_pk_add_f32 v[248:249], v[14:15], v[30:31] neg_lo:[0,1] neg_hi:[0,1]
	v_pk_add_f32 v[6:7], v[242:243], v[246:247]
	ds_write_b64 v226, v[6:7] offset:384
	v_pk_add_f32 v[14:15], v[244:245], v[248:249] op_sel:[0,1] op_sel_hi:[1,0] neg_lo:[0,1]
	ds_write_b64 v226, v[14:15] offset:896
	v_pk_add_f32 v[22:23], v[242:243], v[246:247] neg_lo:[0,1] neg_hi:[0,1]
	ds_write_b64 v226, v[22:23] offset:1408
	v_pk_add_f32 v[30:31], v[244:245], v[248:249] op_sel:[0,1] op_sel_hi:[1,0] neg_hi:[0,1]
	ds_write_b64 v226, v[30:31] offset:1920
	ds_read_b64 v[0:1], v227 offset:0
	ds_read_b64 v[2:3], v227 offset:128
	ds_read_b64 v[4:5], v227 offset:256
	ds_read_b64 v[6:7], v227 offset:384
	ds_read_b64 v[8:9], v227 offset:512
	ds_read_b64 v[10:11], v227 offset:640
	ds_read_b64 v[12:13], v227 offset:768
	ds_read_b64 v[14:15], v227 offset:896
	ds_read_b64 v[16:17], v227 offset:1024
	ds_read_b64 v[18:19], v227 offset:1152
	ds_read_b64 v[20:21], v227 offset:1280
	ds_read_b64 v[22:23], v227 offset:1408
	ds_read_b64 v[24:25], v227 offset:1536
	ds_read_b64 v[26:27], v227 offset:1664
	ds_read_b64 v[28:29], v227 offset:1792
	ds_read_b64 v[30:31], v227 offset:1920
	s_waitcnt lgkmcnt(12)
	v_pk_mul_f32 v[250:251], v[4:5], v[238:239] op_sel:[1,1] op_sel_hi:[0,1]
	v_pk_fma_f32 v[4:5], v[4:5], v[238:239], v[250:251] op_sel:[0,0,0] op_sel_hi:[1,0,1] neg_hi:[0,0,1]
	v_pk_mul_f32 v[250:251], v[2:3], v[236:237] op_sel:[1,1] op_sel_hi:[0,1]
	v_pk_fma_f32 v[2:3], v[2:3], v[236:237], v[250:251] op_sel:[0,0,0] op_sel_hi:[1,0,1] neg_hi:[0,0,1]
	v_pk_mul_f32 v[250:251], v[6:7], v[240:241] op_sel:[1,1] op_sel_hi:[0,1]
	v_pk_fma_f32 v[6:7], v[6:7], v[240:241], v[250:251] op_sel:[0,0,0] op_sel_hi:[1,0,1] neg_hi:[0,0,1]
	v_pk_add_f32 v[242:243], v[0:1], v[4:5]
	v_pk_add_f32 v[244:245], v[0:1], v[4:5] neg_lo:[0,1] neg_hi:[0,1]
	v_pk_add_f32 v[246:247], v[2:3], v[6:7]
	v_pk_add_f32 v[248:249], v[2:3], v[6:7] neg_lo:[0,1] neg_hi:[0,1]
	v_pk_add_f32 v[0:1], v[242:243], v[246:247]
	v_pk_add_f32 v[2:3], v[244:245], v[248:249] op_sel:[0,1] op_sel_hi:[1,0] neg_lo:[0,1]
	v_pk_add_f32 v[4:5], v[242:243], v[246:247] neg_lo:[0,1] neg_hi:[0,1]
	v_pk_add_f32 v[6:7], v[244:245], v[248:249] op_sel:[0,1] op_sel_hi:[1,0] neg_hi:[0,1]
	s_waitcnt lgkmcnt(8)
	v_pk_mul_f32 v[250:251], v[12:13], v[238:239] op_sel:[1,1] op_sel_hi:[0,1]
	v_pk_fma_f32 v[12:13], v[12:13], v[238:239], v[250:251] op_sel:[0,0,0] op_sel_hi:[1,0,1] neg_hi:[0,0,1]
	v_pk_mul_f32 v[250:251], v[10:11], v[236:237] op_sel:[1,1] op_sel_hi:[0,1]
	v_pk_fma_f32 v[10:11], v[10:11], v[236:237], v[250:251] op_sel:[0,0,0] op_sel_hi:[1,0,1] neg_hi:[0,0,1]
	v_pk_mul_f32 v[250:251], v[14:15], v[240:241] op_sel:[1,1] op_sel_hi:[0,1]
	v_pk_fma_f32 v[14:15], v[14:15], v[240:241], v[250:251] op_sel:[0,0,0] op_sel_hi:[1,0,1] neg_hi:[0,0,1]
	v_pk_add_f32 v[242:243], v[8:9], v[12:13]
	v_pk_add_f32 v[244:245], v[8:9], v[12:13] neg_lo:[0,1] neg_hi:[0,1]
	v_pk_add_f32 v[246:247], v[10:11], v[14:15]
	v_pk_add_f32 v[248:249], v[10:11], v[14:15] neg_lo:[0,1] neg_hi:[0,1]
	v_pk_add_f32 v[8:9], v[242:243], v[246:247]
	v_pk_add_f32 v[10:11], v[244:245], v[248:249] op_sel:[0,1] op_sel_hi:[1,0] neg_lo:[0,1]
	v_pk_add_f32 v[12:13], v[242:243], v[246:247] neg_lo:[0,1] neg_hi:[0,1]
	v_pk_add_f32 v[14:15], v[244:245], v[248:249] op_sel:[0,1] op_sel_hi:[1,0] neg_hi:[0,1]
	s_waitcnt lgkmcnt(4)
	v_pk_mul_f32 v[250:251], v[20:21], v[238:239] op_sel:[1,1] op_sel_hi:[0,1]
	v_pk_fma_f32 v[20:21], v[20:21], v[238:239], v[250:251] op_sel:[0,0,0] op_sel_hi:[1,0,1] neg_hi:[0,0,1]
	v_pk_mul_f32 v[250:251], v[18:19], v[236:237] op_sel:[1,1] op_sel_hi:[0,1]
	v_pk_fma_f32 v[18:19], v[18:19], v[236:237], v[250:251] op_sel:[0,0,0] op_sel_hi:[1,0,1] neg_hi:[0,0,1]
	v_pk_mul_f32 v[250:251], v[22:23], v[240:241] op_sel:[1,1] op_sel_hi:[0,1]
	v_pk_fma_f32 v[22:23], v[22:23], v[240:241], v[250:251] op_sel:[0,0,0] op_sel_hi:[1,0,1] neg_hi:[0,0,1]
	v_pk_add_f32 v[242:243], v[16:17], v[20:21]
	v_pk_add_f32 v[244:245], v[16:17], v[20:21] neg_lo:[0,1] neg_hi:[0,1]
	v_pk_add_f32 v[246:247], v[18:19], v[22:23]
	v_pk_add_f32 v[248:249], v[18:19], v[22:23] neg_lo:[0,1] neg_hi:[0,1]
	v_pk_add_f32 v[16:17], v[242:243], v[246:247]
	v_pk_add_f32 v[18:19], v[244:245], v[248:249] op_sel:[0,1] op_sel_hi:[1,0] neg_lo:[0,1]
	v_pk_add_f32 v[20:21], v[242:243], v[246:247] neg_lo:[0,1] neg_hi:[0,1]
	v_pk_add_f32 v[22:23], v[244:245], v[248:249] op_sel:[0,1] op_sel_hi:[1,0] neg_hi:[0,1]
	s_waitcnt lgkmcnt(0)
; HD float2 cmul(float2 a, float2 b){ return make_float2(a.x*b.x - a.y*b.y, a.x*b.y + a.y*b.x); }
; HD float2 cmulc(float2 a, float2 b){ return make_float2(a.x*b.x + a.y*b.y, a.y*b.x - a.x*b.y); }
; template<bool INV, bool NOTW>
; HD void bf4c(float2* Z, int i0, int i1, int i2, int i3, float2 w1, float2 w2, float2 w3){
;   float2 a0=Z[i0], a1=Z[i1], a2=Z[i2], a3=Z[i3];
;   if (INV && !NOTW){ a1=cmulc(a1,w1); a2=cmulc(a2,w2); a3=cmulc(a3,w3); }
;   float2 s02=make_float2(a0.x+a2.x,a0.y+a2.y), d02=make_float2(a0.x-a2.x,a0.y-a2.y);
;   float2 s13=make_float2(a1.x+a3.x,a1.y+a3.y), d13=make_float2(a1.x-a3.x,a1.y-a3.y);
;   float2 y0=make_float2(s02.x+s13.x,s02.y+s13.y), y2=make_float2(s02.x-s13.x,s02.y-s13.y);
;   float2 ym=make_float2(d02.x+d13.y,d02.y-d13.x);
;   float2 yp=make_float2(d02.x-d13.y,d02.y+d13.x);
;   float2 y1, y3;
;   if (INV){ y1=yp; y3=ym; } else if (NOTW){ y1=ym; y3=yp; } else { y1=cmul(ym,w1); y2=cmul(y2,w2); y3=cmul(yp,w3); }
;   Z[i0]=y0; Z[i1]=y1; Z[i2]=y2; Z[i3]=y3;
; }
; template<bool INV, int LQ, bool BARRIER=true>
; HD void fft_pass(float2* Z, const float2* twA, const float2* twB, int tid){
;     ...
;   } else {
;     int j=tid&(q-1); int base0=((tid>>LQ)<<(LQ+2))+j;
;     float2 w1=make_float2(1.f,0.f), w2=w1, w3=w1;
;     if (LQ>0){ int k=j*tws; w1=cmul(twA[k>>6],twB[k&63]); w2=cmul(w1,w1); w3=cmul(w2,w1); }
;     _Pragma("unroll") for (int i=0;i<8;++i){ int base=base0+i*2048; bf4c<INV,(LQ==0)>(Z,base,base+q,base+2*q,base+3*q,w1,w2,w3); }
;   }
;   if (BARRIER) __syncthreads(); else asm volatile("s_waitcnt lgkmcnt(0)" ::: "memory");
; }
; __device__ __forceinline__ void fft_fwd_head(float2* Z, const float2* twA, const float2* twB, int tid){
;   fft_pass<false,10>(Z,twA,twB,tid); fft_pass<false,8>(Z,twA,twB,tid); fft_pass<false,6,false>(Z,twA,twB,tid);
;   fft_pass<false,4,false>(Z,twA,twB,tid); fft_pass<false,2,false>(Z,twA,twB,tid);
; }
; __device__ __forceinline__ void fft_inv_tail(float2* Z, const float2* twA, const float2* twB, int tid){
;   fft_pass<true,2,false>(Z,twA,twB,tid); fft_pass<true,4,false>(Z,twA,twB,tid); fft_pass<true,6>(Z,twA,twB,tid);
;   fft_pass<true,8>(Z,twA,twB,tid); fft_pass<true,10>(Z,twA,twB,tid);
; }
	v_pk_mul_f32 v[250:251], v[28:29], v[238:239] op_sel:[1,1] op_sel_hi:[0,1]
	v_pk_fma_f32 v[28:29], v[28:29], v[238:239], v[250:251] op_sel:[0,0,0] op_sel_hi:[1,0,1] neg_hi:[0,0,1]
	v_pk_mul_f32 v[250:251], v[26:27], v[236:237] op_sel:[1,1] op_sel_hi:[0,1]
	v_pk_fma_f32 v[26:27], v[26:27], v[236:237], v[250:251] op_sel:[0,0,0] op_sel_hi:[1,0,1] neg_hi:[0,0,1]
	v_pk_mul_f32 v[250:251], v[30:31], v[240:241] op_sel:[1,1] op_sel_hi:[0,1]
	v_pk_fma_f32 v[30:31], v[30:31], v[240:241], v[250:251] op_sel:[0,0,0] op_sel_hi:[1,0,1] neg_hi:[0,0,1]
	v_pk_add_f32 v[242:243], v[24:25], v[28:29]
	v_pk_add_f32 v[244:245], v[24:25], v[28:29] neg_lo:[0,1] neg_hi:[0,1]
	v_pk_add_f32 v[246:247], v[26:27], v[30:31]
	v_pk_add_f32 v[248:249], v[26:27], v[30:31] neg_lo:[0,1] neg_hi:[0,1]
	v_pk_add_f32 v[24:25], v[242:243], v[246:247]
	v_pk_add_f32 v[26:27], v[244:245], v[248:249] op_sel:[0,1] op_sel_hi:[1,0] neg_lo:[0,1]
	v_pk_add_f32 v[28:29], v[242:243], v[246:247] neg_lo:[0,1] neg_hi:[0,1]
	v_pk_add_f32 v[30:31], v[244:245], v[248:249] op_sel:[0,1] op_sel_hi:[1,0] neg_hi:[0,1]
	v_pk_mul_f32 v[250:251], v[16:17], v[82:83] op_sel:[1,1] op_sel_hi:[0,1]
	v_pk_fma_f32 v[16:17], v[16:17], v[82:83], v[250:251] op_sel:[0,0,0] op_sel_hi:[1,0,1] neg_hi:[0,0,1]
	v_pk_mul_f32 v[250:251], v[8:9], v[80:81] op_sel:[1,1] op_sel_hi:[0,1]
	v_pk_fma_f32 v[8:9], v[8:9], v[80:81], v[250:251] op_sel:[0,0,0] op_sel_hi:[1,0,1] neg_hi:[0,0,1]
	v_pk_mul_f32 v[250:251], v[24:25], v[84:85] op_sel:[1,1] op_sel_hi:[0,1]
	v_pk_fma_f32 v[24:25], v[24:25], v[84:85], v[250:251] op_sel:[0,0,0] op_sel_hi:[1,0,1] neg_hi:[0,0,1]
	v_pk_add_f32 v[242:243], v[0:1], v[16:17]
	v_pk_add_f32 v[244:245], v[0:1], v[16:17] neg_lo:[0,1] neg_hi:[0,1]
	v_pk_add_f32 v[246:247], v[8:9], v[24:25]
	v_pk_add_f32 v[248:249], v[8:9], v[24:25] neg_lo:[0,1] neg_hi:[0,1]
	v_pk_add_f32 v[0:1], v[242:243], v[246:247]
	ds_write_b64 v227, v[0:1] offset:0
	v_pk_add_f32 v[8:9], v[244:245], v[248:249] op_sel:[0,1] op_sel_hi:[1,0] neg_lo:[0,1]
	ds_write_b64 v227, v[8:9] offset:512
	v_pk_add_f32 v[16:17], v[242:243], v[246:247] neg_lo:[0,1] neg_hi:[0,1]
	ds_write_b64 v227, v[16:17] offset:1024
	v_pk_add_f32 v[24:25], v[244:245], v[248:249] op_sel:[0,1] op_sel_hi:[1,0] neg_hi:[0,1]
	ds_write_b64 v227, v[24:25] offset:1536
	v_pk_mul_f32 v[250:251], v[18:19], v[224:225] op_sel:[1,1] op_sel_hi:[1,0] neg_lo:[0,0] neg_hi:[0,0]
	v_pk_fma_f32 v[18:19], v[18:19], v[224:225], v[250:251] op_sel:[0,0,0] op_sel_hi:[0,1,1] neg_lo:[0,0,1] neg_hi:[0,0,0]
	v_pk_mul_f32 v[250:251], v[18:19], v[82:83] op_sel:[1,1] op_sel_hi:[0,1]
	v_pk_fma_f32 v[18:19], v[18:19], v[82:83], v[250:251] op_sel:[0,0,0] op_sel_hi:[1,0,1] neg_hi:[0,0,1]
	v_pk_mul_f32 v[250:251], v[10:11], v[222:223] op_sel:[1,1] op_sel_hi:[1,0] neg_lo:[0,0] neg_hi:[0,0]
	v_pk_fma_f32 v[10:11], v[10:11], v[222:223], v[250:251] op_sel:[0,0,0] op_sel_hi:[0,1,1] neg_lo:[0,0,1] neg_hi:[0,0,0]
	v_pk_mul_f32 v[250:251], v[10:11], v[80:81] op_sel:[1,1] op_sel_hi:[0,1]
	v_pk_fma_f32 v[10:11], v[10:11], v[80:81], v[250:251] op_sel:[0,0,0] op_sel_hi:[1,0,1] neg_hi:[0,0,1]
	v_pk_mul_f32 v[250:251], v[26:27], v[222:223] op_sel:[1,0] op_sel_hi:[1,1] neg_lo:[0,0] neg_hi:[0,0]
	v_pk_fma_f32 v[26:27], v[26:27], v[222:223], v[250:251] op_sel:[0,1,0] op_sel_hi:[0,0,1] neg_lo:[0,0,1] neg_hi:[0,0,0]
	v_pk_mul_f32 v[250:251], v[26:27], v[84:85] op_sel:[1,1] op_sel_hi:[0,1]
	v_pk_fma_f32 v[26:27], v[26:27], v[84:85], v[250:251] op_sel:[0,0,0] op_sel_hi:[1,0,1] neg_hi:[0,0,1]
	v_pk_add_f32 v[242:243], v[2:3], v[18:19]
	v_pk_add_f32 v[244:245], v[2:3], v[18:19] neg_lo:[0,1] neg_hi:[0,1]
	v_pk_add_f32 v[246:247], v[10:11], v[26:27]
	v_pk_add_f32 v[248:249], v[10:11], v[26:27] neg_lo:[0,1] neg_hi:[0,1]
	v_pk_add_f32 v[2:3], v[242:243], v[246:247]
	ds_write_b64 v227, v[2:3] offset:128
	v_pk_add_f32 v[10:11], v[244:245], v[248:249] op_sel:[0,1] op_sel_hi:[1,0] neg_lo:[0,1]
	ds_write_b64 v227, v[10:11] offset:640
	v_pk_add_f32 v[18:19], v[242:243], v[246:247] neg_lo:[0,1] neg_hi:[0,1]
	ds_write_b64 v227, v[18:19] offset:1152
	v_pk_add_f32 v[26:27], v[244:245], v[248:249] op_sel:[0,1] op_sel_hi:[1,0] neg_hi:[0,1]
	ds_write_b64 v227, v[26:27] offset:1664
	v_pk_add_f32 v[20:21], v[20:21], 0 op_sel:[1,0] op_sel_hi:[0,0] neg_lo:[1,0]
	v_pk_mul_f32 v[250:251], v[20:21], v[82:83] op_sel:[1,1] op_sel_hi:[0,1]
	v_pk_fma_f32 v[20:21], v[20:21], v[82:83], v[250:251] op_sel:[0,0,0] op_sel_hi:[1,0,1] neg_hi:[0,0,1]
	v_pk_mul_f32 v[250:251], v[12:13], v[224:225] op_sel:[1,1] op_sel_hi:[1,0] neg_lo:[0,0] neg_hi:[0,0]
	v_pk_fma_f32 v[12:13], v[12:13], v[224:225], v[250:251] op_sel:[0,0,0] op_sel_hi:[0,1,1] neg_lo:[0,0,1] neg_hi:[0,0,0]
	v_pk_mul_f32 v[250:251], v[12:13], v[80:81] op_sel:[1,1] op_sel_hi:[0,1]
	v_pk_fma_f32 v[12:13], v[12:13], v[80:81], v[250:251] op_sel:[0,0,0] op_sel_hi:[1,0,1] neg_hi:[0,0,1]
	v_pk_mul_f32 v[250:251], v[28:29], v[224:225] op_sel:[1,1] op_sel_hi:[1,0] neg_lo:[0,0] neg_hi:[0,1]
	v_pk_fma_f32 v[28:29], v[28:29], v[224:225], v[250:251] op_sel:[0,0,0] op_sel_hi:[0,1,1] neg_lo:[0,1,1] neg_hi:[0,0,0]
	v_pk_mul_f32 v[250:251], v[28:29], v[84:85] op_sel:[1,1] op_sel_hi:[0,1]
	v_pk_fma_f32 v[28:29], v[28:29], v[84:85], v[250:251] op_sel:[0,0,0] op_sel_hi:[1,0,1] neg_hi:[0,0,1]
	v_pk_add_f32 v[242:243], v[4:5], v[20:21]
	v_pk_add_f32 v[244:245], v[4:5], v[20:21] neg_lo:[0,1] neg_hi:[0,1]
	v_pk_add_f32 v[246:247], v[12:13], v[28:29]
	v_pk_add_f32 v[248:249], v[12:13], v[28:29] neg_lo:[0,1] neg_hi:[0,1]
	v_pk_add_f32 v[4:5], v[242:243], v[246:247]
	ds_write_b64 v227, v[4:5] offset:256
	v_pk_add_f32 v[12:13], v[244:245], v[248:249] op_sel:[0,1] op_sel_hi:[1,0] neg_lo:[0,1]
	ds_write_b64 v227, v[12:13] offset:768
; HD float2 cmul(float2 a, float2 b){ return make_float2(a.x*b.x - a.y*b.y, a.x*b.y + a.y*b.x); }
; HD float2 cmulc(float2 a, float2 b){ return make_float2(a.x*b.x + a.y*b.y, a.y*b.x - a.x*b.y); }
; template<bool INV, bool NOTW>
; HD void bf4c(float2* Z, int i0, int i1, int i2, int i3, float2 w1, float2 w2, float2 w3){
;   float2 a0=Z[i0], a1=Z[i1], a2=Z[i2], a3=Z[i3];
;   if (INV && !NOTW){ a1=cmulc(a1,w1); a2=cmulc(a2,w2); a3=cmulc(a3,w3); }
;   float2 s02=make_float2(a0.x+a2.x,a0.y+a2.y), d02=make_float2(a0.x-a2.x,a0.y-a2.y);
;   float2 s13=make_float2(a1.x+a3.x,a1.y+a3.y), d13=make_float2(a1.x-a3.x,a1.y-a3.y);
;   float2 y0=make_float2(s02.x+s13.x,s02.y+s13.y), y2=make_float2(s02.x-s13.x,s02.y-s13.y);
;   float2 ym=make_float2(d02.x+d13.y,d02.y-d13.x);
;   float2 yp=make_float2(d02.x-d13.y,d02.y+d13.x);
;   float2 y1, y3;
;   if (INV){ y1=yp; y3=ym; } else if (NOTW){ y1=ym; y3=yp; } else { y1=cmul(ym,w1); y2=cmul(y2,w2); y3=cmul(yp,w3); }
;   Z[i0]=y0; Z[i1]=y1; Z[i2]=y2; Z[i3]=y3;
; }
; template<bool INV, int LQ, bool BARRIER=true>
; HD void fft_pass(float2* Z, const float2* twA, const float2* twB, int tid){
;     ...
;   } else {
;     int j=tid&(q-1); int base0=((tid>>LQ)<<(LQ+2))+j;
;     float2 w1=make_float2(1.f,0.f), w2=w1, w3=w1;
;     if (LQ>0){ int k=j*tws; w1=cmul(twA[k>>6],twB[k&63]); w2=cmul(w1,w1); w3=cmul(w2,w1); }
;     _Pragma("unroll") for (int i=0;i<8;++i){ int base=base0+i*2048; bf4c<INV,(LQ==0)>(Z,base,base+q,base+2*q,base+3*q,w1,w2,w3); }
;   }
;   if (BARRIER) __syncthreads(); else asm volatile("s_waitcnt lgkmcnt(0)" ::: "memory");
; }
; __device__ __forceinline__ void fft_fwd_head(float2* Z, const float2* twA, const float2* twB, int tid){
;   fft_pass<false,10>(Z,twA,twB,tid); fft_pass<false,8>(Z,twA,twB,tid); fft_pass<false,6,false>(Z,twA,twB,tid);
;   fft_pass<false,4,false>(Z,twA,twB,tid); fft_pass<false,2,false>(Z,twA,twB,tid);
; }
; __device__ __forceinline__ void fft_inv_tail(float2* Z, const float2* twA, const float2* twB, int tid){
;   fft_pass<true,2,false>(Z,twA,twB,tid); fft_pass<true,4,false>(Z,twA,twB,tid); fft_pass<true,6>(Z,twA,twB,tid);
;   fft_pass<true,8>(Z,twA,twB,tid); fft_pass<true,10>(Z,twA,twB,tid);
; }
	v_pk_add_f32 v[20:21], v[242:243], v[246:247] neg_lo:[0,1] neg_hi:[0,1]
	ds_write_b64 v227, v[20:21] offset:1280
	v_pk_add_f32 v[28:29], v[244:245], v[248:249] op_sel:[0,1] op_sel_hi:[1,0] neg_hi:[0,1]
	ds_write_b64 v227, v[28:29] offset:1792
	v_pk_mul_f32 v[250:251], v[22:23], v[224:225] op_sel:[1,1] op_sel_hi:[1,0] neg_lo:[0,0] neg_hi:[0,1]
	v_pk_fma_f32 v[22:23], v[22:23], v[224:225], v[250:251] op_sel:[0,0,0] op_sel_hi:[0,1,1] neg_lo:[0,1,1] neg_hi:[0,0,0]
	v_pk_mul_f32 v[250:251], v[22:23], v[82:83] op_sel:[1,1] op_sel_hi:[0,1]
	v_pk_fma_f32 v[22:23], v[22:23], v[82:83], v[250:251] op_sel:[0,0,0] op_sel_hi:[1,0,1] neg_hi:[0,0,1]
	v_pk_mul_f32 v[250:251], v[14:15], v[222:223] op_sel:[1,0] op_sel_hi:[1,1] neg_lo:[0,0] neg_hi:[0,0]
	v_pk_fma_f32 v[14:15], v[14:15], v[222:223], v[250:251] op_sel:[0,1,0] op_sel_hi:[0,0,1] neg_lo:[0,0,1] neg_hi:[0,0,0]
	v_pk_mul_f32 v[250:251], v[14:15], v[80:81] op_sel:[1,1] op_sel_hi:[0,1]
	v_pk_fma_f32 v[14:15], v[14:15], v[80:81], v[250:251] op_sel:[0,0,0] op_sel_hi:[1,0,1] neg_hi:[0,0,1]
	v_pk_mul_f32 v[250:251], v[30:31], v[222:223] op_sel:[1,1] op_sel_hi:[1,0] neg_lo:[0,1] neg_hi:[0,1]
	v_pk_fma_f32 v[30:31], v[30:31], v[222:223], v[250:251] op_sel:[0,0,0] op_sel_hi:[0,1,1] neg_lo:[0,1,1] neg_hi:[0,1,0]
	v_pk_mul_f32 v[250:251], v[30:31], v[84:85] op_sel:[1,1] op_sel_hi:[0,1]
	v_pk_fma_f32 v[30:31], v[30:31], v[84:85], v[250:251] op_sel:[0,0,0] op_sel_hi:[1,0,1] neg_hi:[0,0,1]
	v_pk_add_f32 v[242:243], v[6:7], v[22:23]
	v_pk_add_f32 v[244:245], v[6:7], v[22:23] neg_lo:[0,1] neg_hi:[0,1]
	v_pk_add_f32 v[246:247], v[14:15], v[30:31]
	v_pk_add_f32 v[248:249], v[14:15], v[30:31] neg_lo:[0,1] neg_hi:[0,1]
	v_pk_add_f32 v[6:7], v[242:243], v[246:247]
	ds_write_b64 v227, v[6:7] offset:384
	v_pk_add_f32 v[14:15], v[244:245], v[248:249] op_sel:[0,1] op_sel_hi:[1,0] neg_lo:[0,1]
	ds_write_b64 v227, v[14:15] offset:896
	v_pk_add_f32 v[22:23], v[242:243], v[246:247] neg_lo:[0,1] neg_hi:[0,1]
	ds_write_b64 v227, v[22:23] offset:1408
	v_pk_add_f32 v[30:31], v[244:245], v[248:249] op_sel:[0,1] op_sel_hi:[1,0] neg_hi:[0,1]
	ds_write_b64 v227, v[30:31] offset:1920
	s_waitcnt lgkmcnt(0)
	s_barrier
	v_and_b32_e32 v8, 255, v154
	v_lshrrev_b32_e32 v9, 4, v8
	v_lshlrev_b32_e32 v9, 3, v9
	v_add_u32_e32 v9, 0x20800, v9
	v_and_b32_e32 v10, 15, v8
	v_lshlrev_b32_e32 v10, 5, v10
	v_add_u32_e32 v10, 0x20a00, v10
	ds_read_b64 v[0:1], v9
	ds_read_b64 v[2:3], v10
	s_waitcnt lgkmcnt(0)
	v_pk_mul_f32 v[250:251], v[0:1], v[2:3] op_sel:[1,1] op_sel_hi:[1,0]
	v_pk_fma_f32 v[80:81], v[0:1], v[2:3], v[250:251] op_sel:[0,0,0] op_sel_hi:[0,1,1] neg_lo:[0,0,1]
	v_pk_mul_f32 v[250:251], v[80:81], v[80:81] op_sel:[1,1] op_sel_hi:[1,0]
	v_pk_fma_f32 v[82:83], v[80:81], v[80:81], v[250:251] op_sel:[0,0,0] op_sel_hi:[0,1,1] neg_lo:[0,0,1]
	v_pk_mul_f32 v[250:251], v[82:83], v[80:81] op_sel:[1,1] op_sel_hi:[1,0]
	v_pk_fma_f32 v[84:85], v[82:83], v[80:81], v[250:251] op_sel:[0,0,0] op_sel_hi:[0,1,1] neg_lo:[0,0,1]
	v_lshrrev_b32_e32 v9, 2, v8
	v_lshlrev_b32_e32 v9, 3, v9
	v_add_u32_e32 v9, 0x20800, v9
	v_and_b32_e32 v10, 3, v8
	v_lshlrev_b32_e32 v10, 7, v10
	v_add_u32_e32 v10, 0x20a00, v10
	ds_read_b64 v[0:1], v9
	ds_read_b64 v[2:3], v10
	s_waitcnt lgkmcnt(0)
	v_pk_mul_f32 v[250:251], v[0:1], v[2:3] op_sel:[1,1] op_sel_hi:[1,0]
	v_pk_fma_f32 v[236:237], v[0:1], v[2:3], v[250:251] op_sel:[0,0,0] op_sel_hi:[0,1,1] neg_lo:[0,0,1]
	v_pk_mul_f32 v[250:251], v[236:237], v[236:237] op_sel:[1,1] op_sel_hi:[1,0]
	v_pk_fma_f32 v[238:239], v[236:237], v[236:237], v[250:251] op_sel:[0,0,0] op_sel_hi:[0,1,1] neg_lo:[0,0,1]
	v_pk_mul_f32 v[250:251], v[238:239], v[236:237] op_sel:[1,1] op_sel_hi:[1,0]
	v_pk_fma_f32 v[240:241], v[238:239], v[236:237], v[250:251] op_sel:[0,0,0] op_sel_hi:[0,1,1] neg_lo:[0,0,1]
	v_lshrrev_b32_e32 v226, 8, v154
	v_lshlrev_b32_e32 v226, 12, v226
	v_and_b32_e32 v227, 255, v154
	v_add_u32_e32 v226, v226, v227
	v_lshlrev_b32_e32 v226, 3, v226
	v_add_u32_e32 v227, 0x10000, v226
	ds_read_b64 v[0:1], v226 offset:0
	ds_read_b64 v[2:3], v226 offset:2048
	ds_read_b64 v[4:5], v226 offset:4096
	ds_read_b64 v[6:7], v226 offset:6144
	ds_read_b64 v[8:9], v226 offset:8192
	ds_read_b64 v[10:11], v226 offset:10240
	ds_read_b64 v[12:13], v226 offset:12288
	ds_read_b64 v[14:15], v226 offset:14336
	ds_read_b64 v[16:17], v226 offset:16384
	ds_read_b64 v[18:19], v226 offset:18432
	ds_read_b64 v[20:21], v226 offset:20480
	ds_read_b64 v[22:23], v226 offset:22528
	ds_read_b64 v[24:25], v226 offset:24576
	ds_read_b64 v[26:27], v226 offset:26624
	ds_read_b64 v[28:29], v226 offset:28672
	ds_read_b64 v[30:31], v226 offset:30720
	s_waitcnt lgkmcnt(12)
	v_pk_mul_f32 v[250:251], v[4:5], v[238:239] op_sel:[1,1] op_sel_hi:[0,1]
	v_pk_fma_f32 v[4:5], v[4:5], v[238:239], v[250:251] op_sel:[0,0,0] op_sel_hi:[1,0,1] neg_hi:[0,0,1]
	v_pk_mul_f32 v[250:251], v[2:3], v[236:237] op_sel:[1,1] op_sel_hi:[0,1]
	v_pk_fma_f32 v[2:3], v[2:3], v[236:237], v[250:251] op_sel:[0,0,0] op_sel_hi:[1,0,1] neg_hi:[0,0,1]
	v_pk_mul_f32 v[250:251], v[6:7], v[240:241] op_sel:[1,1] op_sel_hi:[0,1]
	v_pk_fma_f32 v[6:7], v[6:7], v[240:241], v[250:251] op_sel:[0,0,0] op_sel_hi:[1,0,1] neg_hi:[0,0,1]
	v_pk_add_f32 v[242:243], v[0:1], v[4:5]
	v_pk_add_f32 v[244:245], v[0:1], v[4:5] neg_lo:[0,1] neg_hi:[0,1]
	v_pk_add_f32 v[246:247], v[2:3], v[6:7]
	v_pk_add_f32 v[248:249], v[2:3], v[6:7] neg_lo:[0,1] neg_hi:[0,1]
	v_pk_add_f32 v[0:1], v[242:243], v[246:247]
	v_pk_add_f32 v[2:3], v[244:245], v[248:249] op_sel:[0,1] op_sel_hi:[1,0] neg_lo:[0,1]
	v_pk_add_f32 v[4:5], v[242:243], v[246:247] neg_lo:[0,1] neg_hi:[0,1]
	v_pk_add_f32 v[6:7], v[244:245], v[248:249] op_sel:[0,1] op_sel_hi:[1,0] neg_hi:[0,1]
	s_waitcnt lgkmcnt(8)
; HD float2 cmul(float2 a, float2 b){ return make_float2(a.x*b.x - a.y*b.y, a.x*b.y + a.y*b.x); }
; HD float2 cmulc(float2 a, float2 b){ return make_float2(a.x*b.x + a.y*b.y, a.y*b.x - a.x*b.y); }
; template<bool INV, bool NOTW>
; HD void bf4c(float2* Z, int i0, int i1, int i2, int i3, float2 w1, float2 w2, float2 w3){
;   float2 a0=Z[i0], a1=Z[i1], a2=Z[i2], a3=Z[i3];
;   if (INV && !NOTW){ a1=cmulc(a1,w1); a2=cmulc(a2,w2); a3=cmulc(a3,w3); }
;   float2 s02=make_float2(a0.x+a2.x,a0.y+a2.y), d02=make_float2(a0.x-a2.x,a0.y-a2.y);
;   float2 s13=make_float2(a1.x+a3.x,a1.y+a3.y), d13=make_float2(a1.x-a3.x,a1.y-a3.y);
;   float2 y0=make_float2(s02.x+s13.x,s02.y+s13.y), y2=make_float2(s02.x-s13.x,s02.y-s13.y);
;   float2 ym=make_float2(d02.x+d13.y,d02.y-d13.x);
;   float2 yp=make_float2(d02.x-d13.y,d02.y+d13.x);
;   float2 y1, y3;
;   if (INV){ y1=yp; y3=ym; } else if (NOTW){ y1=ym; y3=yp; } else { y1=cmul(ym,w1); y2=cmul(y2,w2); y3=cmul(yp,w3); }
;   Z[i0]=y0; Z[i1]=y1; Z[i2]=y2; Z[i3]=y3;
; }
; template<bool INV, int LQ, bool BARRIER=true>
; HD void fft_pass(float2* Z, const float2* twA, const float2* twB, int tid){
;     ...
;   } else {
;     int j=tid&(q-1); int base0=((tid>>LQ)<<(LQ+2))+j;
;     float2 w1=make_float2(1.f,0.f), w2=w1, w3=w1;
;     if (LQ>0){ int k=j*tws; w1=cmul(twA[k>>6],twB[k&63]); w2=cmul(w1,w1); w3=cmul(w2,w1); }
;     _Pragma("unroll") for (int i=0;i<8;++i){ int base=base0+i*2048; bf4c<INV,(LQ==0)>(Z,base,base+q,base+2*q,base+3*q,w1,w2,w3); }
;   }
;   if (BARRIER) __syncthreads(); else asm volatile("s_waitcnt lgkmcnt(0)" ::: "memory");
; }
; __device__ __forceinline__ void fft_fwd_head(float2* Z, const float2* twA, const float2* twB, int tid){
;   fft_pass<false,10>(Z,twA,twB,tid); fft_pass<false,8>(Z,twA,twB,tid); fft_pass<false,6,false>(Z,twA,twB,tid);
;   fft_pass<false,4,false>(Z,twA,twB,tid); fft_pass<false,2,false>(Z,twA,twB,tid);
; }
; __device__ __forceinline__ void fft_inv_tail(float2* Z, const float2* twA, const float2* twB, int tid){
;   fft_pass<true,2,false>(Z,twA,twB,tid); fft_pass<true,4,false>(Z,twA,twB,tid); fft_pass<true,6>(Z,twA,twB,tid);
;   fft_pass<true,8>(Z,twA,twB,tid); fft_pass<true,10>(Z,twA,twB,tid);
; }
	v_pk_mul_f32 v[250:251], v[12:13], v[238:239] op_sel:[1,1] op_sel_hi:[0,1]
	v_pk_fma_f32 v[12:13], v[12:13], v[238:239], v[250:251] op_sel:[0,0,0] op_sel_hi:[1,0,1] neg_hi:[0,0,1]
	v_pk_mul_f32 v[250:251], v[10:11], v[236:237] op_sel:[1,1] op_sel_hi:[0,1]
	v_pk_fma_f32 v[10:11], v[10:11], v[236:237], v[250:251] op_sel:[0,0,0] op_sel_hi:[1,0,1] neg_hi:[0,0,1]
	v_pk_mul_f32 v[250:251], v[14:15], v[240:241] op_sel:[1,1] op_sel_hi:[0,1]
	v_pk_fma_f32 v[14:15], v[14:15], v[240:241], v[250:251] op_sel:[0,0,0] op_sel_hi:[1,0,1] neg_hi:[0,0,1]
	v_pk_add_f32 v[242:243], v[8:9], v[12:13]
	v_pk_add_f32 v[244:245], v[8:9], v[12:13] neg_lo:[0,1] neg_hi:[0,1]
	v_pk_add_f32 v[246:247], v[10:11], v[14:15]
	v_pk_add_f32 v[248:249], v[10:11], v[14:15] neg_lo:[0,1] neg_hi:[0,1]
	v_pk_add_f32 v[8:9], v[242:243], v[246:247]
	v_pk_add_f32 v[10:11], v[244:245], v[248:249] op_sel:[0,1] op_sel_hi:[1,0] neg_lo:[0,1]
	v_pk_add_f32 v[12:13], v[242:243], v[246:247] neg_lo:[0,1] neg_hi:[0,1]
	v_pk_add_f32 v[14:15], v[244:245], v[248:249] op_sel:[0,1] op_sel_hi:[1,0] neg_hi:[0,1]
	s_waitcnt lgkmcnt(4)
	v_pk_mul_f32 v[250:251], v[20:21], v[238:239] op_sel:[1,1] op_sel_hi:[0,1]
	v_pk_fma_f32 v[20:21], v[20:21], v[238:239], v[250:251] op_sel:[0,0,0] op_sel_hi:[1,0,1] neg_hi:[0,0,1]
	v_pk_mul_f32 v[250:251], v[18:19], v[236:237] op_sel:[1,1] op_sel_hi:[0,1]
	v_pk_fma_f32 v[18:19], v[18:19], v[236:237], v[250:251] op_sel:[0,0,0] op_sel_hi:[1,0,1] neg_hi:[0,0,1]
	v_pk_mul_f32 v[250:251], v[22:23], v[240:241] op_sel:[1,1] op_sel_hi:[0,1]
	v_pk_fma_f32 v[22:23], v[22:23], v[240:241], v[250:251] op_sel:[0,0,0] op_sel_hi:[1,0,1] neg_hi:[0,0,1]
	v_pk_add_f32 v[242:243], v[16:17], v[20:21]
	v_pk_add_f32 v[244:245], v[16:17], v[20:21] neg_lo:[0,1] neg_hi:[0,1]
	v_pk_add_f32 v[246:247], v[18:19], v[22:23]
	v_pk_add_f32 v[248:249], v[18:19], v[22:23] neg_lo:[0,1] neg_hi:[0,1]
	v_pk_add_f32 v[16:17], v[242:243], v[246:247]
	v_pk_add_f32 v[18:19], v[244:245], v[248:249] op_sel:[0,1] op_sel_hi:[1,0] neg_lo:[0,1]
	v_pk_add_f32 v[20:21], v[242:243], v[246:247] neg_lo:[0,1] neg_hi:[0,1]
	v_pk_add_f32 v[22:23], v[244:245], v[248:249] op_sel:[0,1] op_sel_hi:[1,0] neg_hi:[0,1]
	s_waitcnt lgkmcnt(0)
	v_pk_mul_f32 v[250:251], v[28:29], v[238:239] op_sel:[1,1] op_sel_hi:[0,1]
	v_pk_fma_f32 v[28:29], v[28:29], v[238:239], v[250:251] op_sel:[0,0,0] op_sel_hi:[1,0,1] neg_hi:[0,0,1]
	v_pk_mul_f32 v[250:251], v[26:27], v[236:237] op_sel:[1,1] op_sel_hi:[0,1]
	v_pk_fma_f32 v[26:27], v[26:27], v[236:237], v[250:251] op_sel:[0,0,0] op_sel_hi:[1,0,1] neg_hi:[0,0,1]
	v_pk_mul_f32 v[250:251], v[30:31], v[240:241] op_sel:[1,1] op_sel_hi:[0,1]
	v_pk_fma_f32 v[30:31], v[30:31], v[240:241], v[250:251] op_sel:[0,0,0] op_sel_hi:[1,0,1] neg_hi:[0,0,1]
	v_pk_add_f32 v[242:243], v[24:25], v[28:29]
	v_pk_add_f32 v[244:245], v[24:25], v[28:29] neg_lo:[0,1] neg_hi:[0,1]
	v_pk_add_f32 v[246:247], v[26:27], v[30:31]
	v_pk_add_f32 v[248:249], v[26:27], v[30:31] neg_lo:[0,1] neg_hi:[0,1]
	v_pk_add_f32 v[24:25], v[242:243], v[246:247]
	v_pk_add_f32 v[26:27], v[244:245], v[248:249] op_sel:[0,1] op_sel_hi:[1,0] neg_lo:[0,1]
	v_pk_add_f32 v[28:29], v[242:243], v[246:247] neg_lo:[0,1] neg_hi:[0,1]
	v_pk_add_f32 v[30:31], v[244:245], v[248:249] op_sel:[0,1] op_sel_hi:[1,0] neg_hi:[0,1]
	v_pk_mul_f32 v[250:251], v[16:17], v[82:83] op_sel:[1,1] op_sel_hi:[0,1]
	v_pk_fma_f32 v[16:17], v[16:17], v[82:83], v[250:251] op_sel:[0,0,0] op_sel_hi:[1,0,1] neg_hi:[0,0,1]
	v_pk_mul_f32 v[250:251], v[8:9], v[80:81] op_sel:[1,1] op_sel_hi:[0,1]
	v_pk_fma_f32 v[8:9], v[8:9], v[80:81], v[250:251] op_sel:[0,0,0] op_sel_hi:[1,0,1] neg_hi:[0,0,1]
	v_pk_mul_f32 v[250:251], v[24:25], v[84:85] op_sel:[1,1] op_sel_hi:[0,1]
	v_pk_fma_f32 v[24:25], v[24:25], v[84:85], v[250:251] op_sel:[0,0,0] op_sel_hi:[1,0,1] neg_hi:[0,0,1]
	v_pk_add_f32 v[242:243], v[0:1], v[16:17]
	v_pk_add_f32 v[244:245], v[0:1], v[16:17] neg_lo:[0,1] neg_hi:[0,1]
	v_pk_add_f32 v[246:247], v[8:9], v[24:25]
	v_pk_add_f32 v[248:249], v[8:9], v[24:25] neg_lo:[0,1] neg_hi:[0,1]
	v_pk_add_f32 v[0:1], v[242:243], v[246:247]
	ds_write_b64 v226, v[0:1] offset:0
	v_pk_add_f32 v[8:9], v[244:245], v[248:249] op_sel:[0,1] op_sel_hi:[1,0] neg_lo:[0,1]
	ds_write_b64 v226, v[8:9] offset:8192
	v_pk_add_f32 v[16:17], v[242:243], v[246:247] neg_lo:[0,1] neg_hi:[0,1]
	ds_write_b64 v226, v[16:17] offset:16384
	v_pk_add_f32 v[24:25], v[244:245], v[248:249] op_sel:[0,1] op_sel_hi:[1,0] neg_hi:[0,1]
	ds_write_b64 v226, v[24:25] offset:24576
	v_pk_mul_f32 v[250:251], v[18:19], v[224:225] op_sel:[1,1] op_sel_hi:[1,0] neg_lo:[0,0] neg_hi:[0,0]
	v_pk_fma_f32 v[18:19], v[18:19], v[224:225], v[250:251] op_sel:[0,0,0] op_sel_hi:[0,1,1] neg_lo:[0,0,1] neg_hi:[0,0,0]
	v_pk_mul_f32 v[250:251], v[18:19], v[82:83] op_sel:[1,1] op_sel_hi:[0,1]
	v_pk_fma_f32 v[18:19], v[18:19], v[82:83], v[250:251] op_sel:[0,0,0] op_sel_hi:[1,0,1] neg_hi:[0,0,1]
	v_pk_mul_f32 v[250:251], v[10:11], v[222:223] op_sel:[1,1] op_sel_hi:[1,0] neg_lo:[0,0] neg_hi:[0,0]
	v_pk_fma_f32 v[10:11], v[10:11], v[222:223], v[250:251] op_sel:[0,0,0] op_sel_hi:[0,1,1] neg_lo:[0,0,1] neg_hi:[0,0,0]
	v_pk_mul_f32 v[250:251], v[10:11], v[80:81] op_sel:[1,1] op_sel_hi:[0,1]
	v_pk_fma_f32 v[10:11], v[10:11], v[80:81], v[250:251] op_sel:[0,0,0] op_sel_hi:[1,0,1] neg_hi:[0,0,1]
	v_pk_mul_f32 v[250:251], v[26:27], v[222:223] op_sel:[1,0] op_sel_hi:[1,1] neg_lo:[0,0] neg_hi:[0,0]
	v_pk_fma_f32 v[26:27], v[26:27], v[222:223], v[250:251] op_sel:[0,1,0] op_sel_hi:[0,0,1] neg_lo:[0,0,1] neg_hi:[0,0,0]
	v_pk_mul_f32 v[250:251], v[26:27], v[84:85] op_sel:[1,1] op_sel_hi:[0,1]
	v_pk_fma_f32 v[26:27], v[26:27], v[84:85], v[250:251] op_sel:[0,0,0] op_sel_hi:[1,0,1] neg_hi:[0,0,1]
; HD float2 cmul(float2 a, float2 b){ return make_float2(a.x*b.x - a.y*b.y, a.x*b.y + a.y*b.x); }
; HD float2 cmulc(float2 a, float2 b){ return make_float2(a.x*b.x + a.y*b.y, a.y*b.x - a.x*b.y); }
; template<bool INV, bool NOTW>
; HD void bf4c(float2* Z, int i0, int i1, int i2, int i3, float2 w1, float2 w2, float2 w3){
;   float2 a0=Z[i0], a1=Z[i1], a2=Z[i2], a3=Z[i3];
;   if (INV && !NOTW){ a1=cmulc(a1,w1); a2=cmulc(a2,w2); a3=cmulc(a3,w3); }
;   float2 s02=make_float2(a0.x+a2.x,a0.y+a2.y), d02=make_float2(a0.x-a2.x,a0.y-a2.y);
;   float2 s13=make_float2(a1.x+a3.x,a1.y+a3.y), d13=make_float2(a1.x-a3.x,a1.y-a3.y);
;   float2 y0=make_float2(s02.x+s13.x,s02.y+s13.y), y2=make_float2(s02.x-s13.x,s02.y-s13.y);
;   float2 ym=make_float2(d02.x+d13.y,d02.y-d13.x);
;   float2 yp=make_float2(d02.x-d13.y,d02.y+d13.x);
;   float2 y1, y3;
;   if (INV){ y1=yp; y3=ym; } else if (NOTW){ y1=ym; y3=yp; } else { y1=cmul(ym,w1); y2=cmul(y2,w2); y3=cmul(yp,w3); }
;   Z[i0]=y0; Z[i1]=y1; Z[i2]=y2; Z[i3]=y3;
; }
; template<bool INV, int LQ, bool BARRIER=true>
; HD void fft_pass(float2* Z, const float2* twA, const float2* twB, int tid){
;     ...
;   } else {
;     int j=tid&(q-1); int base0=((tid>>LQ)<<(LQ+2))+j;
;     float2 w1=make_float2(1.f,0.f), w2=w1, w3=w1;
;     if (LQ>0){ int k=j*tws; w1=cmul(twA[k>>6],twB[k&63]); w2=cmul(w1,w1); w3=cmul(w2,w1); }
;     _Pragma("unroll") for (int i=0;i<8;++i){ int base=base0+i*2048; bf4c<INV,(LQ==0)>(Z,base,base+q,base+2*q,base+3*q,w1,w2,w3); }
;   }
;   if (BARRIER) __syncthreads(); else asm volatile("s_waitcnt lgkmcnt(0)" ::: "memory");
; }
; __device__ __forceinline__ void fft_fwd_head(float2* Z, const float2* twA, const float2* twB, int tid){
;   fft_pass<false,10>(Z,twA,twB,tid); fft_pass<false,8>(Z,twA,twB,tid); fft_pass<false,6,false>(Z,twA,twB,tid);
;   fft_pass<false,4,false>(Z,twA,twB,tid); fft_pass<false,2,false>(Z,twA,twB,tid);
; }
; __device__ __forceinline__ void fft_inv_tail(float2* Z, const float2* twA, const float2* twB, int tid){
;   fft_pass<true,2,false>(Z,twA,twB,tid); fft_pass<true,4,false>(Z,twA,twB,tid); fft_pass<true,6>(Z,twA,twB,tid);
;   fft_pass<true,8>(Z,twA,twB,tid); fft_pass<true,10>(Z,twA,twB,tid);
; }
	v_pk_add_f32 v[242:243], v[2:3], v[18:19]
	v_pk_add_f32 v[244:245], v[2:3], v[18:19] neg_lo:[0,1] neg_hi:[0,1]
	v_pk_add_f32 v[246:247], v[10:11], v[26:27]
	v_pk_add_f32 v[248:249], v[10:11], v[26:27] neg_lo:[0,1] neg_hi:[0,1]
	v_pk_add_f32 v[2:3], v[242:243], v[246:247]
	ds_write_b64 v226, v[2:3] offset:2048
	v_pk_add_f32 v[10:11], v[244:245], v[248:249] op_sel:[0,1] op_sel_hi:[1,0] neg_lo:[0,1]
	ds_write_b64 v226, v[10:11] offset:10240
	v_pk_add_f32 v[18:19], v[242:243], v[246:247] neg_lo:[0,1] neg_hi:[0,1]
	ds_write_b64 v226, v[18:19] offset:18432
	v_pk_add_f32 v[26:27], v[244:245], v[248:249] op_sel:[0,1] op_sel_hi:[1,0] neg_hi:[0,1]
	ds_write_b64 v226, v[26:27] offset:26624
	v_pk_add_f32 v[20:21], v[20:21], 0 op_sel:[1,0] op_sel_hi:[0,0] neg_lo:[1,0]
	v_pk_mul_f32 v[250:251], v[20:21], v[82:83] op_sel:[1,1] op_sel_hi:[0,1]
	v_pk_fma_f32 v[20:21], v[20:21], v[82:83], v[250:251] op_sel:[0,0,0] op_sel_hi:[1,0,1] neg_hi:[0,0,1]
	v_pk_mul_f32 v[250:251], v[12:13], v[224:225] op_sel:[1,1] op_sel_hi:[1,0] neg_lo:[0,0] neg_hi:[0,0]
	v_pk_fma_f32 v[12:13], v[12:13], v[224:225], v[250:251] op_sel:[0,0,0] op_sel_hi:[0,1,1] neg_lo:[0,0,1] neg_hi:[0,0,0]
	v_pk_mul_f32 v[250:251], v[12:13], v[80:81] op_sel:[1,1] op_sel_hi:[0,1]
	v_pk_fma_f32 v[12:13], v[12:13], v[80:81], v[250:251] op_sel:[0,0,0] op_sel_hi:[1,0,1] neg_hi:[0,0,1]
	v_pk_mul_f32 v[250:251], v[28:29], v[224:225] op_sel:[1,1] op_sel_hi:[1,0] neg_lo:[0,0] neg_hi:[0,1]
	v_pk_fma_f32 v[28:29], v[28:29], v[224:225], v[250:251] op_sel:[0,0,0] op_sel_hi:[0,1,1] neg_lo:[0,1,1] neg_hi:[0,0,0]
	v_pk_mul_f32 v[250:251], v[28:29], v[84:85] op_sel:[1,1] op_sel_hi:[0,1]
	v_pk_fma_f32 v[28:29], v[28:29], v[84:85], v[250:251] op_sel:[0,0,0] op_sel_hi:[1,0,1] neg_hi:[0,0,1]
	v_pk_add_f32 v[242:243], v[4:5], v[20:21]
	v_pk_add_f32 v[244:245], v[4:5], v[20:21] neg_lo:[0,1] neg_hi:[0,1]
	v_pk_add_f32 v[246:247], v[12:13], v[28:29]
	v_pk_add_f32 v[248:249], v[12:13], v[28:29] neg_lo:[0,1] neg_hi:[0,1]
	v_pk_add_f32 v[4:5], v[242:243], v[246:247]
	ds_write_b64 v226, v[4:5] offset:4096
	v_pk_add_f32 v[12:13], v[244:245], v[248:249] op_sel:[0,1] op_sel_hi:[1,0] neg_lo:[0,1]
	ds_write_b64 v226, v[12:13] offset:12288
	v_pk_add_f32 v[20:21], v[242:243], v[246:247] neg_lo:[0,1] neg_hi:[0,1]
	ds_write_b64 v226, v[20:21] offset:20480
	v_pk_add_f32 v[28:29], v[244:245], v[248:249] op_sel:[0,1] op_sel_hi:[1,0] neg_hi:[0,1]
	ds_write_b64 v226, v[28:29] offset:28672
	v_pk_mul_f32 v[250:251], v[22:23], v[224:225] op_sel:[1,1] op_sel_hi:[1,0] neg_lo:[0,0] neg_hi:[0,1]
	v_pk_fma_f32 v[22:23], v[22:23], v[224:225], v[250:251] op_sel:[0,0,0] op_sel_hi:[0,1,1] neg_lo:[0,1,1] neg_hi:[0,0,0]
	v_pk_mul_f32 v[250:251], v[22:23], v[82:83] op_sel:[1,1] op_sel_hi:[0,1]
	v_pk_fma_f32 v[22:23], v[22:23], v[82:83], v[250:251] op_sel:[0,0,0] op_sel_hi:[1,0,1] neg_hi:[0,0,1]
	v_pk_mul_f32 v[250:251], v[14:15], v[222:223] op_sel:[1,0] op_sel_hi:[1,1] neg_lo:[0,0] neg_hi:[0,0]
	v_pk_fma_f32 v[14:15], v[14:15], v[222:223], v[250:251] op_sel:[0,1,0] op_sel_hi:[0,0,1] neg_lo:[0,0,1] neg_hi:[0,0,0]
	v_pk_mul_f32 v[250:251], v[14:15], v[80:81] op_sel:[1,1] op_sel_hi:[0,1]
	v_pk_fma_f32 v[14:15], v[14:15], v[80:81], v[250:251] op_sel:[0,0,0] op_sel_hi:[1,0,1] neg_hi:[0,0,1]
	v_pk_mul_f32 v[250:251], v[30:31], v[222:223] op_sel:[1,1] op_sel_hi:[1,0] neg_lo:[0,1] neg_hi:[0,1]
	v_pk_fma_f32 v[30:31], v[30:31], v[222:223], v[250:251] op_sel:[0,0,0] op_sel_hi:[0,1,1] neg_lo:[0,1,1] neg_hi:[0,1,0]
	v_pk_mul_f32 v[250:251], v[30:31], v[84:85] op_sel:[1,1] op_sel_hi:[0,1]
	v_pk_fma_f32 v[30:31], v[30:31], v[84:85], v[250:251] op_sel:[0,0,0] op_sel_hi:[1,0,1] neg_hi:[0,0,1]
	v_pk_add_f32 v[242:243], v[6:7], v[22:23]
	v_pk_add_f32 v[244:245], v[6:7], v[22:23] neg_lo:[0,1] neg_hi:[0,1]
	v_pk_add_f32 v[246:247], v[14:15], v[30:31]
	v_pk_add_f32 v[248:249], v[14:15], v[30:31] neg_lo:[0,1] neg_hi:[0,1]
	v_pk_add_f32 v[6:7], v[242:243], v[246:247]
	ds_write_b64 v226, v[6:7] offset:6144
	v_pk_add_f32 v[14:15], v[244:245], v[248:249] op_sel:[0,1] op_sel_hi:[1,0] neg_lo:[0,1]
	ds_write_b64 v226, v[14:15] offset:14336
	v_pk_add_f32 v[22:23], v[242:243], v[246:247] neg_lo:[0,1] neg_hi:[0,1]
	ds_write_b64 v226, v[22:23] offset:22528
	v_pk_add_f32 v[30:31], v[244:245], v[248:249] op_sel:[0,1] op_sel_hi:[1,0] neg_hi:[0,1]
	ds_write_b64 v226, v[30:31] offset:30720
	ds_read_b64 v[0:1], v227 offset:0
	ds_read_b64 v[2:3], v227 offset:2048
	ds_read_b64 v[4:5], v227 offset:4096
	ds_read_b64 v[6:7], v227 offset:6144
	ds_read_b64 v[8:9], v227 offset:8192
	ds_read_b64 v[10:11], v227 offset:10240
	ds_read_b64 v[12:13], v227 offset:12288
	ds_read_b64 v[14:15], v227 offset:14336
	ds_read_b64 v[16:17], v227 offset:16384
	ds_read_b64 v[18:19], v227 offset:18432
	ds_read_b64 v[20:21], v227 offset:20480
	ds_read_b64 v[22:23], v227 offset:22528
	ds_read_b64 v[24:25], v227 offset:24576
	ds_read_b64 v[26:27], v227 offset:26624
	ds_read_b64 v[28:29], v227 offset:28672
	ds_read_b64 v[30:31], v227 offset:30720
	s_waitcnt lgkmcnt(12)
	v_pk_mul_f32 v[250:251], v[4:5], v[238:239] op_sel:[1,1] op_sel_hi:[0,1]
	v_pk_fma_f32 v[4:5], v[4:5], v[238:239], v[250:251] op_sel:[0,0,0] op_sel_hi:[1,0,1] neg_hi:[0,0,1]
	v_pk_mul_f32 v[250:251], v[2:3], v[236:237] op_sel:[1,1] op_sel_hi:[0,1]
	v_pk_fma_f32 v[2:3], v[2:3], v[236:237], v[250:251] op_sel:[0,0,0] op_sel_hi:[1,0,1] neg_hi:[0,0,1]
	v_pk_mul_f32 v[250:251], v[6:7], v[240:241] op_sel:[1,1] op_sel_hi:[0,1]
	v_pk_fma_f32 v[6:7], v[6:7], v[240:241], v[250:251] op_sel:[0,0,0] op_sel_hi:[1,0,1] neg_hi:[0,0,1]
	v_pk_add_f32 v[242:243], v[0:1], v[4:5]
	v_pk_add_f32 v[244:245], v[0:1], v[4:5] neg_lo:[0,1] neg_hi:[0,1]
	v_pk_add_f32 v[246:247], v[2:3], v[6:7]
	v_pk_add_f32 v[248:249], v[2:3], v[6:7] neg_lo:[0,1] neg_hi:[0,1]
	v_pk_add_f32 v[0:1], v[242:243], v[246:247]
	v_pk_add_f32 v[2:3], v[244:245], v[248:249] op_sel:[0,1] op_sel_hi:[1,0] neg_lo:[0,1]
	v_pk_add_f32 v[4:5], v[242:243], v[246:247] neg_lo:[0,1] neg_hi:[0,1]
	v_pk_add_f32 v[6:7], v[244:245], v[248:249] op_sel:[0,1] op_sel_hi:[1,0] neg_hi:[0,1]
	s_waitcnt lgkmcnt(8)
; HD float2 cmul(float2 a, float2 b){ return make_float2(a.x*b.x - a.y*b.y, a.x*b.y + a.y*b.x); }
; HD float2 cmulc(float2 a, float2 b){ return make_float2(a.x*b.x + a.y*b.y, a.y*b.x - a.x*b.y); }
; template<bool INV, bool NOTW>
; HD void bf4c(float2* Z, int i0, int i1, int i2, int i3, float2 w1, float2 w2, float2 w3){
;   float2 a0=Z[i0], a1=Z[i1], a2=Z[i2], a3=Z[i3];
;   if (INV && !NOTW){ a1=cmulc(a1,w1); a2=cmulc(a2,w2); a3=cmulc(a3,w3); }
;   float2 s02=make_float2(a0.x+a2.x,a0.y+a2.y), d02=make_float2(a0.x-a2.x,a0.y-a2.y);
;   float2 s13=make_float2(a1.x+a3.x,a1.y+a3.y), d13=make_float2(a1.x-a3.x,a1.y-a3.y);
;   float2 y0=make_float2(s02.x+s13.x,s02.y+s13.y), y2=make_float2(s02.x-s13.x,s02.y-s13.y);
;   float2 ym=make_float2(d02.x+d13.y,d02.y-d13.x);
;   float2 yp=make_float2(d02.x-d13.y,d02.y+d13.x);
;   float2 y1, y3;
;   if (INV){ y1=yp; y3=ym; } else if (NOTW){ y1=ym; y3=yp; } else { y1=cmul(ym,w1); y2=cmul(y2,w2); y3=cmul(yp,w3); }
;   Z[i0]=y0; Z[i1]=y1; Z[i2]=y2; Z[i3]=y3;
; }
; template<bool INV, int LQ, bool BARRIER=true>
; HD void fft_pass(float2* Z, const float2* twA, const float2* twB, int tid){
;     ...
;   } else {
;     int j=tid&(q-1); int base0=((tid>>LQ)<<(LQ+2))+j;
;     float2 w1=make_float2(1.f,0.f), w2=w1, w3=w1;
;     if (LQ>0){ int k=j*tws; w1=cmul(twA[k>>6],twB[k&63]); w2=cmul(w1,w1); w3=cmul(w2,w1); }
;     _Pragma("unroll") for (int i=0;i<8;++i){ int base=base0+i*2048; bf4c<INV,(LQ==0)>(Z,base,base+q,base+2*q,base+3*q,w1,w2,w3); }
;   }
;   if (BARRIER) __syncthreads(); else asm volatile("s_waitcnt lgkmcnt(0)" ::: "memory");
; }
; __device__ __forceinline__ void fft_fwd_head(float2* Z, const float2* twA, const float2* twB, int tid){
;   fft_pass<false,10>(Z,twA,twB,tid); fft_pass<false,8>(Z,twA,twB,tid); fft_pass<false,6,false>(Z,twA,twB,tid);
;   fft_pass<false,4,false>(Z,twA,twB,tid); fft_pass<false,2,false>(Z,twA,twB,tid);
; }
; __device__ __forceinline__ void fft_inv_tail(float2* Z, const float2* twA, const float2* twB, int tid){
;   fft_pass<true,2,false>(Z,twA,twB,tid); fft_pass<true,4,false>(Z,twA,twB,tid); fft_pass<true,6>(Z,twA,twB,tid);
;   fft_pass<true,8>(Z,twA,twB,tid); fft_pass<true,10>(Z,twA,twB,tid);
; }
	v_pk_mul_f32 v[250:251], v[12:13], v[238:239] op_sel:[1,1] op_sel_hi:[0,1]
	v_pk_fma_f32 v[12:13], v[12:13], v[238:239], v[250:251] op_sel:[0,0,0] op_sel_hi:[1,0,1] neg_hi:[0,0,1]
	v_pk_mul_f32 v[250:251], v[10:11], v[236:237] op_sel:[1,1] op_sel_hi:[0,1]
	v_pk_fma_f32 v[10:11], v[10:11], v[236:237], v[250:251] op_sel:[0,0,0] op_sel_hi:[1,0,1] neg_hi:[0,0,1]
	v_pk_mul_f32 v[250:251], v[14:15], v[240:241] op_sel:[1,1] op_sel_hi:[0,1]
	v_pk_fma_f32 v[14:15], v[14:15], v[240:241], v[250:251] op_sel:[0,0,0] op_sel_hi:[1,0,1] neg_hi:[0,0,1]
	v_pk_add_f32 v[242:243], v[8:9], v[12:13]
	v_pk_add_f32 v[244:245], v[8:9], v[12:13] neg_lo:[0,1] neg_hi:[0,1]
	v_pk_add_f32 v[246:247], v[10:11], v[14:15]
	v_pk_add_f32 v[248:249], v[10:11], v[14:15] neg_lo:[0,1] neg_hi:[0,1]
	v_pk_add_f32 v[8:9], v[242:243], v[246:247]
	v_pk_add_f32 v[10:11], v[244:245], v[248:249] op_sel:[0,1] op_sel_hi:[1,0] neg_lo:[0,1]
	v_pk_add_f32 v[12:13], v[242:243], v[246:247] neg_lo:[0,1] neg_hi:[0,1]
	v_pk_add_f32 v[14:15], v[244:245], v[248:249] op_sel:[0,1] op_sel_hi:[1,0] neg_hi:[0,1]
	s_waitcnt lgkmcnt(4)
	v_pk_mul_f32 v[250:251], v[20:21], v[238:239] op_sel:[1,1] op_sel_hi:[0,1]
	v_pk_fma_f32 v[20:21], v[20:21], v[238:239], v[250:251] op_sel:[0,0,0] op_sel_hi:[1,0,1] neg_hi:[0,0,1]
	v_pk_mul_f32 v[250:251], v[18:19], v[236:237] op_sel:[1,1] op_sel_hi:[0,1]
	v_pk_fma_f32 v[18:19], v[18:19], v[236:237], v[250:251] op_sel:[0,0,0] op_sel_hi:[1,0,1] neg_hi:[0,0,1]
	v_pk_mul_f32 v[250:251], v[22:23], v[240:241] op_sel:[1,1] op_sel_hi:[0,1]
	v_pk_fma_f32 v[22:23], v[22:23], v[240:241], v[250:251] op_sel:[0,0,0] op_sel_hi:[1,0,1] neg_hi:[0,0,1]
	v_pk_add_f32 v[242:243], v[16:17], v[20:21]
	v_pk_add_f32 v[244:245], v[16:17], v[20:21] neg_lo:[0,1] neg_hi:[0,1]
	v_pk_add_f32 v[246:247], v[18:19], v[22:23]
	v_pk_add_f32 v[248:249], v[18:19], v[22:23] neg_lo:[0,1] neg_hi:[0,1]
	v_pk_add_f32 v[16:17], v[242:243], v[246:247]
	v_pk_add_f32 v[18:19], v[244:245], v[248:249] op_sel:[0,1] op_sel_hi:[1,0] neg_lo:[0,1]
	v_pk_add_f32 v[20:21], v[242:243], v[246:247] neg_lo:[0,1] neg_hi:[0,1]
	v_pk_add_f32 v[22:23], v[244:245], v[248:249] op_sel:[0,1] op_sel_hi:[1,0] neg_hi:[0,1]
	s_waitcnt lgkmcnt(0)
	v_pk_mul_f32 v[250:251], v[28:29], v[238:239] op_sel:[1,1] op_sel_hi:[0,1]
	v_pk_fma_f32 v[28:29], v[28:29], v[238:239], v[250:251] op_sel:[0,0,0] op_sel_hi:[1,0,1] neg_hi:[0,0,1]
	v_pk_mul_f32 v[250:251], v[26:27], v[236:237] op_sel:[1,1] op_sel_hi:[0,1]
	v_pk_fma_f32 v[26:27], v[26:27], v[236:237], v[250:251] op_sel:[0,0,0] op_sel_hi:[1,0,1] neg_hi:[0,0,1]
	v_pk_mul_f32 v[250:251], v[30:31], v[240:241] op_sel:[1,1] op_sel_hi:[0,1]
	v_pk_fma_f32 v[30:31], v[30:31], v[240:241], v[250:251] op_sel:[0,0,0] op_sel_hi:[1,0,1] neg_hi:[0,0,1]
	v_pk_add_f32 v[242:243], v[24:25], v[28:29]
	v_pk_add_f32 v[244:245], v[24:25], v[28:29] neg_lo:[0,1] neg_hi:[0,1]
	v_pk_add_f32 v[246:247], v[26:27], v[30:31]
	v_pk_add_f32 v[248:249], v[26:27], v[30:31] neg_lo:[0,1] neg_hi:[0,1]
	v_pk_add_f32 v[24:25], v[242:243], v[246:247]
	v_pk_add_f32 v[26:27], v[244:245], v[248:249] op_sel:[0,1] op_sel_hi:[1,0] neg_lo:[0,1]
	v_pk_add_f32 v[28:29], v[242:243], v[246:247] neg_lo:[0,1] neg_hi:[0,1]
	v_pk_add_f32 v[30:31], v[244:245], v[248:249] op_sel:[0,1] op_sel_hi:[1,0] neg_hi:[0,1]
	v_pk_mul_f32 v[250:251], v[16:17], v[82:83] op_sel:[1,1] op_sel_hi:[0,1]
	v_pk_fma_f32 v[16:17], v[16:17], v[82:83], v[250:251] op_sel:[0,0,0] op_sel_hi:[1,0,1] neg_hi:[0,0,1]
	v_pk_mul_f32 v[250:251], v[8:9], v[80:81] op_sel:[1,1] op_sel_hi:[0,1]
	v_pk_fma_f32 v[8:9], v[8:9], v[80:81], v[250:251] op_sel:[0,0,0] op_sel_hi:[1,0,1] neg_hi:[0,0,1]
	v_pk_mul_f32 v[250:251], v[24:25], v[84:85] op_sel:[1,1] op_sel_hi:[0,1]
	v_pk_fma_f32 v[24:25], v[24:25], v[84:85], v[250:251] op_sel:[0,0,0] op_sel_hi:[1,0,1] neg_hi:[0,0,1]
	v_pk_add_f32 v[242:243], v[0:1], v[16:17]
	v_pk_add_f32 v[244:245], v[0:1], v[16:17] neg_lo:[0,1] neg_hi:[0,1]
	v_pk_add_f32 v[246:247], v[8:9], v[24:25]
	v_pk_add_f32 v[248:249], v[8:9], v[24:25] neg_lo:[0,1] neg_hi:[0,1]
	v_pk_add_f32 v[0:1], v[242:243], v[246:247]
	ds_write_b64 v227, v[0:1] offset:0
	v_pk_add_f32 v[8:9], v[244:245], v[248:249] op_sel:[0,1] op_sel_hi:[1,0] neg_lo:[0,1]
	ds_write_b64 v227, v[8:9] offset:8192
	v_pk_add_f32 v[16:17], v[242:243], v[246:247] neg_lo:[0,1] neg_hi:[0,1]
	ds_write_b64 v227, v[16:17] offset:16384
	v_pk_add_f32 v[24:25], v[244:245], v[248:249] op_sel:[0,1] op_sel_hi:[1,0] neg_hi:[0,1]
	ds_write_b64 v227, v[24:25] offset:24576
	v_pk_mul_f32 v[250:251], v[18:19], v[224:225] op_sel:[1,1] op_sel_hi:[1,0] neg_lo:[0,0] neg_hi:[0,0]
	v_pk_fma_f32 v[18:19], v[18:19], v[224:225], v[250:251] op_sel:[0,0,0] op_sel_hi:[0,1,1] neg_lo:[0,0,1] neg_hi:[0,0,0]
	v_pk_mul_f32 v[250:251], v[18:19], v[82:83] op_sel:[1,1] op_sel_hi:[0,1]
	v_pk_fma_f32 v[18:19], v[18:19], v[82:83], v[250:251] op_sel:[0,0,0] op_sel_hi:[1,0,1] neg_hi:[0,0,1]
	v_pk_mul_f32 v[250:251], v[10:11], v[222:223] op_sel:[1,1] op_sel_hi:[1,0] neg_lo:[0,0] neg_hi:[0,0]
	v_pk_fma_f32 v[10:11], v[10:11], v[222:223], v[250:251] op_sel:[0,0,0] op_sel_hi:[0,1,1] neg_lo:[0,0,1] neg_hi:[0,0,0]
	v_pk_mul_f32 v[250:251], v[10:11], v[80:81] op_sel:[1,1] op_sel_hi:[0,1]
	v_pk_fma_f32 v[10:11], v[10:11], v[80:81], v[250:251] op_sel:[0,0,0] op_sel_hi:[1,0,1] neg_hi:[0,0,1]
	v_pk_mul_f32 v[250:251], v[26:27], v[222:223] op_sel:[1,0] op_sel_hi:[1,1] neg_lo:[0,0] neg_hi:[0,0]
	v_pk_fma_f32 v[26:27], v[26:27], v[222:223], v[250:251] op_sel:[0,1,0] op_sel_hi:[0,0,1] neg_lo:[0,0,1] neg_hi:[0,0,0]
	v_pk_mul_f32 v[250:251], v[26:27], v[84:85] op_sel:[1,1] op_sel_hi:[0,1]
	v_pk_fma_f32 v[26:27], v[26:27], v[84:85], v[250:251] op_sel:[0,0,0] op_sel_hi:[1,0,1] neg_hi:[0,0,1]
; HD float2 cmul(float2 a, float2 b){ return make_float2(a.x*b.x - a.y*b.y, a.x*b.y + a.y*b.x); }
; HD float2 cmulc(float2 a, float2 b){ return make_float2(a.x*b.x + a.y*b.y, a.y*b.x - a.x*b.y); }
; template<bool INV, bool NOTW>
; HD void bf4c(float2* Z, int i0, int i1, int i2, int i3, float2 w1, float2 w2, float2 w3){
;   float2 a0=Z[i0], a1=Z[i1], a2=Z[i2], a3=Z[i3];
;   if (INV && !NOTW){ a1=cmulc(a1,w1); a2=cmulc(a2,w2); a3=cmulc(a3,w3); }
;   float2 s02=make_float2(a0.x+a2.x,a0.y+a2.y), d02=make_float2(a0.x-a2.x,a0.y-a2.y);
;   float2 s13=make_float2(a1.x+a3.x,a1.y+a3.y), d13=make_float2(a1.x-a3.x,a1.y-a3.y);
;   float2 y0=make_float2(s02.x+s13.x,s02.y+s13.y), y2=make_float2(s02.x-s13.x,s02.y-s13.y);
;   float2 ym=make_float2(d02.x+d13.y,d02.y-d13.x);
;   float2 yp=make_float2(d02.x-d13.y,d02.y+d13.x);
;   float2 y1, y3;
;   if (INV){ y1=yp; y3=ym; } else if (NOTW){ y1=ym; y3=yp; } else { y1=cmul(ym,w1); y2=cmul(y2,w2); y3=cmul(yp,w3); }
;   Z[i0]=y0; Z[i1]=y1; Z[i2]=y2; Z[i3]=y3;
; }
; template<bool INV, int LQ, bool BARRIER=true>
; HD void fft_pass(float2* Z, const float2* twA, const float2* twB, int tid){
;     ...
;   } else {
;     int j=tid&(q-1); int base0=((tid>>LQ)<<(LQ+2))+j;
;     float2 w1=make_float2(1.f,0.f), w2=w1, w3=w1;
;     if (LQ>0){ int k=j*tws; w1=cmul(twA[k>>6],twB[k&63]); w2=cmul(w1,w1); w3=cmul(w2,w1); }
;     _Pragma("unroll") for (int i=0;i<8;++i){ int base=base0+i*2048; bf4c<INV,(LQ==0)>(Z,base,base+q,base+2*q,base+3*q,w1,w2,w3); }
;   }
;   if (BARRIER) __syncthreads(); else asm volatile("s_waitcnt lgkmcnt(0)" ::: "memory");
; }
; __device__ __forceinline__ void fft_fwd_head(float2* Z, const float2* twA, const float2* twB, int tid){
;   fft_pass<false,10>(Z,twA,twB,tid); fft_pass<false,8>(Z,twA,twB,tid); fft_pass<false,6,false>(Z,twA,twB,tid);
;   fft_pass<false,4,false>(Z,twA,twB,tid); fft_pass<false,2,false>(Z,twA,twB,tid);
; }
; __device__ __forceinline__ void fft_inv_tail(float2* Z, const float2* twA, const float2* twB, int tid){
;   fft_pass<true,2,false>(Z,twA,twB,tid); fft_pass<true,4,false>(Z,twA,twB,tid); fft_pass<true,6>(Z,twA,twB,tid);
;   fft_pass<true,8>(Z,twA,twB,tid); fft_pass<true,10>(Z,twA,twB,tid);
; }
	v_pk_add_f32 v[242:243], v[2:3], v[18:19]
	v_pk_add_f32 v[244:245], v[2:3], v[18:19] neg_lo:[0,1] neg_hi:[0,1]
	v_pk_add_f32 v[246:247], v[10:11], v[26:27]
	v_pk_add_f32 v[248:249], v[10:11], v[26:27] neg_lo:[0,1] neg_hi:[0,1]
	v_pk_add_f32 v[2:3], v[242:243], v[246:247]
	ds_write_b64 v227, v[2:3] offset:2048
	v_pk_add_f32 v[10:11], v[244:245], v[248:249] op_sel:[0,1] op_sel_hi:[1,0] neg_lo:[0,1]
	ds_write_b64 v227, v[10:11] offset:10240
	v_pk_add_f32 v[18:19], v[242:243], v[246:247] neg_lo:[0,1] neg_hi:[0,1]
	ds_write_b64 v227, v[18:19] offset:18432
	v_pk_add_f32 v[26:27], v[244:245], v[248:249] op_sel:[0,1] op_sel_hi:[1,0] neg_hi:[0,1]
	ds_write_b64 v227, v[26:27] offset:26624
	v_pk_add_f32 v[20:21], v[20:21], 0 op_sel:[1,0] op_sel_hi:[0,0] neg_lo:[1,0]
	v_pk_mul_f32 v[250:251], v[20:21], v[82:83] op_sel:[1,1] op_sel_hi:[0,1]
	v_pk_fma_f32 v[20:21], v[20:21], v[82:83], v[250:251] op_sel:[0,0,0] op_sel_hi:[1,0,1] neg_hi:[0,0,1]
	v_pk_mul_f32 v[250:251], v[12:13], v[224:225] op_sel:[1,1] op_sel_hi:[1,0] neg_lo:[0,0] neg_hi:[0,0]
	v_pk_fma_f32 v[12:13], v[12:13], v[224:225], v[250:251] op_sel:[0,0,0] op_sel_hi:[0,1,1] neg_lo:[0,0,1] neg_hi:[0,0,0]
	v_pk_mul_f32 v[250:251], v[12:13], v[80:81] op_sel:[1,1] op_sel_hi:[0,1]
	v_pk_fma_f32 v[12:13], v[12:13], v[80:81], v[250:251] op_sel:[0,0,0] op_sel_hi:[1,0,1] neg_hi:[0,0,1]
	v_pk_mul_f32 v[250:251], v[28:29], v[224:225] op_sel:[1,1] op_sel_hi:[1,0] neg_lo:[0,0] neg_hi:[0,1]
	v_pk_fma_f32 v[28:29], v[28:29], v[224:225], v[250:251] op_sel:[0,0,0] op_sel_hi:[0,1,1] neg_lo:[0,1,1] neg_hi:[0,0,0]
	v_pk_mul_f32 v[250:251], v[28:29], v[84:85] op_sel:[1,1] op_sel_hi:[0,1]
	v_pk_fma_f32 v[28:29], v[28:29], v[84:85], v[250:251] op_sel:[0,0,0] op_sel_hi:[1,0,1] neg_hi:[0,0,1]
	v_pk_add_f32 v[242:243], v[4:5], v[20:21]
	v_pk_add_f32 v[244:245], v[4:5], v[20:21] neg_lo:[0,1] neg_hi:[0,1]
	v_pk_add_f32 v[246:247], v[12:13], v[28:29]
	v_pk_add_f32 v[248:249], v[12:13], v[28:29] neg_lo:[0,1] neg_hi:[0,1]
	v_pk_add_f32 v[4:5], v[242:243], v[246:247]
	ds_write_b64 v227, v[4:5] offset:4096
	v_pk_add_f32 v[12:13], v[244:245], v[248:249] op_sel:[0,1] op_sel_hi:[1,0] neg_lo:[0,1]
	ds_write_b64 v227, v[12:13] offset:12288
	v_pk_add_f32 v[20:21], v[242:243], v[246:247] neg_lo:[0,1] neg_hi:[0,1]
	ds_write_b64 v227, v[20:21] offset:20480
	v_pk_add_f32 v[28:29], v[244:245], v[248:249] op_sel:[0,1] op_sel_hi:[1,0] neg_hi:[0,1]
	ds_write_b64 v227, v[28:29] offset:28672
	v_pk_mul_f32 v[250:251], v[22:23], v[224:225] op_sel:[1,1] op_sel_hi:[1,0] neg_lo:[0,0] neg_hi:[0,1]
	v_pk_fma_f32 v[22:23], v[22:23], v[224:225], v[250:251] op_sel:[0,0,0] op_sel_hi:[0,1,1] neg_lo:[0,1,1] neg_hi:[0,0,0]
	v_pk_mul_f32 v[250:251], v[22:23], v[82:83] op_sel:[1,1] op_sel_hi:[0,1]
	v_pk_fma_f32 v[22:23], v[22:23], v[82:83], v[250:251] op_sel:[0,0,0] op_sel_hi:[1,0,1] neg_hi:[0,0,1]
	v_pk_mul_f32 v[250:251], v[14:15], v[222:223] op_sel:[1,0] op_sel_hi:[1,1] neg_lo:[0,0] neg_hi:[0,0]
	v_pk_fma_f32 v[14:15], v[14:15], v[222:223], v[250:251] op_sel:[0,1,0] op_sel_hi:[0,0,1] neg_lo:[0,0,1] neg_hi:[0,0,0]
	v_pk_mul_f32 v[250:251], v[14:15], v[80:81] op_sel:[1,1] op_sel_hi:[0,1]
	v_pk_fma_f32 v[14:15], v[14:15], v[80:81], v[250:251] op_sel:[0,0,0] op_sel_hi:[1,0,1] neg_hi:[0,0,1]
	v_pk_mul_f32 v[250:251], v[30:31], v[222:223] op_sel:[1,1] op_sel_hi:[1,0] neg_lo:[0,1] neg_hi:[0,1]
	v_pk_fma_f32 v[30:31], v[30:31], v[222:223], v[250:251] op_sel:[0,0,0] op_sel_hi:[0,1,1] neg_lo:[0,1,1] neg_hi:[0,1,0]
	v_pk_mul_f32 v[250:251], v[30:31], v[84:85] op_sel:[1,1] op_sel_hi:[0,1]
	v_pk_fma_f32 v[30:31], v[30:31], v[84:85], v[250:251] op_sel:[0,0,0] op_sel_hi:[1,0,1] neg_hi:[0,0,1]
	v_pk_add_f32 v[242:243], v[6:7], v[22:23]
	v_pk_add_f32 v[244:245], v[6:7], v[22:23] neg_lo:[0,1] neg_hi:[0,1]
	v_pk_add_f32 v[246:247], v[14:15], v[30:31]
	v_pk_add_f32 v[248:249], v[14:15], v[30:31] neg_lo:[0,1] neg_hi:[0,1]
	v_pk_add_f32 v[6:7], v[242:243], v[246:247]
	ds_write_b64 v227, v[6:7] offset:6144
	v_pk_add_f32 v[14:15], v[244:245], v[248:249] op_sel:[0,1] op_sel_hi:[1,0] neg_lo:[0,1]
	ds_write_b64 v227, v[14:15] offset:14336
	v_pk_add_f32 v[22:23], v[242:243], v[246:247] neg_lo:[0,1] neg_hi:[0,1]
	ds_write_b64 v227, v[22:23] offset:22528
	v_pk_add_f32 v[30:31], v[244:245], v[248:249] op_sel:[0,1] op_sel_hi:[1,0] neg_hi:[0,1]
	ds_write_b64 v227, v[30:31] offset:30720
	s_waitcnt lgkmcnt(0)
	s_barrier
	s_mov_b64 s[12:13], -1
	s_and_b64 vcc, exec, s[50:51]
	s_cbranch_vccz .LBB0_1340
; __device__ __forceinline__ float bf2f(u16 h){ return __uint_as_float(((unsigned)h)<<16); }
; HD float2 cmul(float2 a, float2 b){ return make_float2(a.x*b.x - a.y*b.y, a.x*b.y + a.y*b.x); }
; HD float2 cmulc(float2 a, float2 b){ return make_float2(a.x*b.x + a.y*b.y, a.y*b.x - a.x*b.y); }
; HD void inv12_half(const float2* Z, const float2* twA, const float2* twB, int t, float2& x0, float2& x1){
;   float2 w1=cmul(twA[t>>6],twB[t&63]), w2=cmul(w1,w1), w3=cmul(w2,w1);
;   float2 b0=Z[t], b1=cmulc(Z[t+4096],w1), b2=cmulc(Z[t+8192],w2), b3=cmulc(Z[t+12288],w3);
;   float2 s02=make_float2(b0.x+b2.x,b0.y+b2.y), d02=make_float2(b0.x-b2.x,b0.y-b2.y);
;   float2 s13=make_float2(b1.x+b3.x,b1.y+b3.y), d13=make_float2(b1.x-b3.x,b1.y-b3.y);
;   x0=make_float2(s02.x+s13.x,s02.y+s13.y);
;   x1=make_float2(d02.x-d13.y,d02.y+d13.x);
; }
; __device__ __forceinline__ void phase_hyena(KP kp_, int hf){ asm volatile("" : "+s"(kp_)); const Params p=load_params(kp_);
;     ...
;         } else { int tq=tid; asm volatile("" : "+v"(tq));
;           _Pragma("unroll 4") for (int i=0;i<8;++i){ int tb=tq+512*i; float2 xr[2]; inv12_half(Z,twA,twB,tb,xr[0],xr[1]);
;             _Pragma("unroll") for (int hh=0;hh<2;++hh){ int t=tb+hh*4096;
;               float x0=hconv3(r2,t,wb0,wb1,wb2,bb_), x1=hconv3(r2+8192,t,wb0,wb1,wb2,bb_);
;               float2 y=xr[hh]; y.x*=(1.f/16384.f); y.y*=(1.f/16384.f); float2 z1=Zs[t];
;               float o0=x0*(y.x+z1.x*bias1)*bf2f(rz[t]); float o1=x1*(y.y+z1.y*bias1)*bf2f(rz[8192+t]);
;               ybT[(size_t)c*16384+t]=f2bf(o0); ybT[(size_t)c*16384+8192+t]=f2bf(o1); } }
	s_waitcnt vmcnt(0)
	v_mov_b32_e32 v228, 0
	v_mov_b32_e32 v229, 0
	v_mov_b32_e32 v230, 0
	v_mov_b32_e32 v231, 0
	v_mov_b32_e32 v232, 0
	v_mov_b32_e32 v233, 0
	v_mov_b32_e32 v234, 0
	v_mov_b32_e32 v235, 0
	v_mov_b32_e32 v240, 0
	v_mov_b32_e32 v241, 0
	v_mov_b32_e32 v242, 0
	v_mov_b32_e32 v243, 0
	v_mov_b32_e32 v244, 0
	v_mov_b32_e32 v245, 0
	v_mov_b32_e32 v246, 0
	v_mov_b32_e32 v247, 0
	v_lshlrev_b32_e32 v0, 1, v86
	v_add_u32_e32 v1, 0x1000, v0
	v_add_u32_e32 v2, 0x2000, v0
	v_add_u32_e32 v4, 0x3000, v0
	v_lshlrev_b32_e32 v5, 3, v86
	v_mov_b32_e32 v8, v5
	v_add_u32_e32 v9, 0x10000, v5
	v_lshrrev_b32_e32 v7, 6, v86
	v_lshl_add_u32 v7, v7, 3, s88
	v_and_b32_e32 v108, 63, v86
	v_lshl_add_u32 v108, v108, 3, s91
	ds_read_b64 v[10:11], v108
	s_add_u32 s12, s72, 0x4000
	s_addc_u32 s13, s73, 0
	s_add_u32 s50, s80, 0x8000
	s_addc_u32 s51, s81, 0
	v_mov_b32_e32 v107, 0
	v_mov_b32_e32 v160, 0x38800000
	v_mov_b32_e32 v161, 0x38800000
	v_mov_b32_e32 v106, v0
	v_lshl_add_u64 v[110:111], v[54:55], 0, v[106:107]
	v_lshl_add_u64 v[118:119], v[56:57], 0, v[106:107]
	v_mov_b32_e32 v106, v1
	v_lshl_add_u64 v[112:113], v[54:55], 0, v[106:107]
	v_lshl_add_u64 v[120:121], v[56:57], 0, v[106:107]
	v_mov_b32_e32 v106, v2
	v_lshl_add_u64 v[114:115], v[54:55], 0, v[106:107]
	v_lshl_add_u64 v[122:123], v[56:57], 0, v[106:107]
	v_mov_b32_e32 v106, v4
	v_lshl_add_u64 v[116:117], v[54:55], 0, v[106:107]
	v_lshl_add_u64 v[124:125], v[56:57], 0, v[106:107]
	global_load_short_d16_hi v228, v0, s[96:97] offset:0
	global_load_short_d16_hi v229, v0, s[74:75] offset:0
	global_load_short_d16_hi v232, v0, s[72:73] offset:0
	global_load_short_d16_hi v233, v0, s[12:13] offset:0
	global_load_short_d16_hi v230, v2, s[96:97] offset:0
	global_load_short_d16_hi v231, v2, s[74:75] offset:0
	global_load_short_d16_hi v234, v2, s[72:73] offset:0
	global_load_short_d16_hi v235, v2, s[12:13] offset:0
	v_mov_b32_e32 v6, v5
	global_load_dwordx2 v[236:237], v6, s[80:81] sc1
	global_load_dwordx2 v[238:239], v6, s[50:51] sc1
	ds_read_b64 v[12:13], v7 offset:0
	ds_read_b64 v[14:15], v8 offset:0
	ds_read_b64 v[16:17], v8 offset:32768
	ds_read_b64 v[18:19], v9 offset:0
	ds_read_b64 v[20:21], v9 offset:32768
	global_load_short_d16_hi v240, v0, s[96:97] offset:1024
	global_load_short_d16_hi v241, v0, s[74:75] offset:1024
	global_load_short_d16_hi v244, v0, s[72:73] offset:1024
	global_load_short_d16_hi v245, v0, s[12:13] offset:1024
	global_load_short_d16_hi v242, v2, s[96:97] offset:1024
	global_load_short_d16_hi v243, v2, s[74:75] offset:1024
	global_load_short_d16_hi v246, v2, s[72:73] offset:1024
	global_load_short_d16_hi v247, v2, s[12:13] offset:1024
	v_add_u32_e32 v6, 0x1000, v5
	global_load_dwordx2 v[248:249], v6, s[80:81] sc1
	global_load_dwordx2 v[250:251], v6, s[50:51] sc1
	ds_read_b64 v[58:59], v7 offset:64
	ds_read_b64 v[60:61], v8 offset:4096
	ds_read_b64 v[62:63], v8 offset:36864
	ds_read_b64 v[64:65], v9 offset:4096
	ds_read_b64 v[66:67], v9 offset:36864
	s_waitcnt lgkmcnt(5)
	v_pk_mul_f32 v[222:223], v[12:13], v[10:11] op_sel:[1,1] op_sel_hi:[1,0]
	v_pk_fma_f32 v[22:23], v[12:13], v[10:11], v[222:223] op_sel:[0,0,0] op_sel_hi:[0,1,1] neg_lo:[0,0,1]
	v_pk_mul_f32 v[222:223], v[22:23], v[22:23] op_sel:[1,1] op_sel_hi:[1,0]
	v_pk_fma_f32 v[24:25], v[22:23], v[22:23], v[222:223] op_sel:[0,0,0] op_sel_hi:[0,1,1] neg_lo:[0,0,1]
	v_pk_mul_f32 v[222:223], v[24:25], v[22:23] op_sel:[1,1] op_sel_hi:[1,0]
	v_pk_fma_f32 v[26:27], v[24:25], v[22:23], v[222:223] op_sel:[0,0,0] op_sel_hi:[0,1,1] neg_lo:[0,0,1]
	v_pk_mul_f32 v[222:223], v[16:17], v[22:23] op_sel:[1,1] op_sel_hi:[0,1]
	v_pk_fma_f32 v[28:29], v[16:17], v[22:23], v[222:223] op_sel:[0,0,0] op_sel_hi:[1,0,1] neg_hi:[0,0,1]
	v_pk_mul_f32 v[222:223], v[18:19], v[24:25] op_sel:[1,1] op_sel_hi:[0,1]
	v_pk_fma_f32 v[30:31], v[18:19], v[24:25], v[222:223] op_sel:[0,0,0] op_sel_hi:[1,0,1] neg_hi:[0,0,1]
	v_pk_mul_f32 v[222:223], v[20:21], v[26:27] op_sel:[1,1] op_sel_hi:[0,1]
	v_pk_fma_f32 v[68:69], v[20:21], v[26:27], v[222:223] op_sel:[0,0,0] op_sel_hi:[1,0,1] neg_hi:[0,0,1]
	v_pk_add_f32 v[70:71], v[14:15], v[30:31]
	v_pk_add_f32 v[72:73], v[14:15], v[30:31] neg_lo:[0,1] neg_hi:[0,1]
	v_pk_add_f32 v[74:75], v[28:29], v[68:69]
	v_pk_add_f32 v[80:81], v[28:29], v[68:69] neg_lo:[0,1] neg_hi:[0,1]
	v_pk_add_f32 v[82:83], v[70:71], v[74:75]
	v_pk_add_f32 v[84:85], v[72:73], v[80:81] op_sel:[0,1] op_sel_hi:[1,0] neg_lo:[0,1]
	s_waitcnt vmcnt(10)
	v_pk_mul_f32 v[226:227], v[228:229], v[88:89] op_sel_hi:[1,0]
	v_fmac_f32_dpp v226, v228, v87 wave_shr:1 row_mask:0xf bank_mask:0xf
	v_fmac_f32_dpp v227, v229, v87 wave_shr:1 row_mask:0xf bank_mask:0xf
	v_fmac_f32_dpp v226, v228, v89 wave_shl:1 row_mask:0xf bank_mask:0xf
	v_fmac_f32_dpp v227, v229, v89 wave_shl:1 row_mask:0xf bank_mask:0xf
	v_pk_add_f32 v[150:151], v[226:227], v[90:91] op_sel_hi:[1,0]
	v_pk_mul_f32 v[226:227], v[230:231], v[88:89] op_sel_hi:[1,0]
	v_fmac_f32_dpp v226, v230, v87 wave_shr:1 row_mask:0xf bank_mask:0xf
	v_fmac_f32_dpp v227, v231, v87 wave_shr:1 row_mask:0xf bank_mask:0xf
	v_fmac_f32_dpp v226, v230, v89 wave_shl:1 row_mask:0xf bank_mask:0xf
	v_fmac_f32_dpp v227, v231, v89 wave_shl:1 row_mask:0xf bank_mask:0xf
	v_pk_add_f32 v[152:153], v[226:227], v[90:91] op_sel_hi:[1,0]
	v_pk_mul_f32 v[158:159], v[236:237], v[90:91] op_sel:[0,1] op_sel_hi:[1,1]
	v_pk_fma_f32 v[158:159], v[82:83], v[160:161], v[158:159]
	v_pk_mul_f32 v[158:159], v[150:151], v[158:159]
	v_pk_mul_f32 v[158:159], v[158:159], v[232:233]
	v_cvt_pk_bf16_f32 v224, v158, v159
	global_store_short v[110:111], v224, off offset:0
	global_store_short_d16_hi v[118:119], v224, off offset:0
	v_pk_mul_f32 v[158:159], v[238:239], v[90:91] op_sel:[0,1] op_sel_hi:[1,1]
	v_pk_fma_f32 v[158:159], v[84:85], v[160:161], v[158:159]
	v_pk_mul_f32 v[158:159], v[152:153], v[158:159]
	v_pk_mul_f32 v[158:159], v[158:159], v[234:235]
	v_cvt_pk_bf16_f32 v224, v158, v159
	global_store_short v[114:115], v224, off offset:0
	global_store_short_d16_hi v[122:123], v224, off offset:0
	global_load_short_d16_hi v228, v0, s[96:97] offset:2048
	global_load_short_d16_hi v229, v0, s[74:75] offset:2048
	global_load_short_d16_hi v232, v0, s[72:73] offset:2048
	global_load_short_d16_hi v233, v0, s[12:13] offset:2048
	global_load_short_d16_hi v230, v2, s[96:97] offset:2048
	global_load_short_d16_hi v231, v2, s[74:75] offset:2048
	global_load_short_d16_hi v234, v2, s[72:73] offset:2048
	global_load_short_d16_hi v235, v2, s[12:13] offset:2048
	v_add_u32_e32 v6, 0x2000, v5
	global_load_dwordx2 v[236:237], v6, s[80:81] sc1
	global_load_dwordx2 v[238:239], v6, s[50:51] sc1
	ds_read_b64 v[12:13], v7 offset:128
	ds_read_b64 v[14:15], v8 offset:8192
	ds_read_b64 v[16:17], v8 offset:40960
	ds_read_b64 v[18:19], v9 offset:8192
	ds_read_b64 v[20:21], v9 offset:40960
	s_waitcnt lgkmcnt(5)
; __device__ __forceinline__ float bf2f(u16 h){ return __uint_as_float(((unsigned)h)<<16); }
; HD float2 cmul(float2 a, float2 b){ return make_float2(a.x*b.x - a.y*b.y, a.x*b.y + a.y*b.x); }
; HD float2 cmulc(float2 a, float2 b){ return make_float2(a.x*b.x + a.y*b.y, a.y*b.x - a.x*b.y); }
; HD void inv12_half(const float2* Z, const float2* twA, const float2* twB, int t, float2& x0, float2& x1){
;   float2 w1=cmul(twA[t>>6],twB[t&63]), w2=cmul(w1,w1), w3=cmul(w2,w1);
;   float2 b0=Z[t], b1=cmulc(Z[t+4096],w1), b2=cmulc(Z[t+8192],w2), b3=cmulc(Z[t+12288],w3);
;   float2 s02=make_float2(b0.x+b2.x,b0.y+b2.y), d02=make_float2(b0.x-b2.x,b0.y-b2.y);
;   float2 s13=make_float2(b1.x+b3.x,b1.y+b3.y), d13=make_float2(b1.x-b3.x,b1.y-b3.y);
;   x0=make_float2(s02.x+s13.x,s02.y+s13.y);
;   x1=make_float2(d02.x-d13.y,d02.y+d13.x);
; }
; __device__ __forceinline__ void phase_hyena(KP kp_, int hf){ asm volatile("" : "+s"(kp_)); const Params p=load_params(kp_);
;     ...
;         } else { int tq=tid; asm volatile("" : "+v"(tq));
;           _Pragma("unroll 4") for (int i=0;i<8;++i){ int tb=tq+512*i; float2 xr[2]; inv12_half(Z,twA,twB,tb,xr[0],xr[1]);
;             _Pragma("unroll") for (int hh=0;hh<2;++hh){ int t=tb+hh*4096;
;               float x0=hconv3(r2,t,wb0,wb1,wb2,bb_), x1=hconv3(r2+8192,t,wb0,wb1,wb2,bb_);
;               float2 y=xr[hh]; y.x*=(1.f/16384.f); y.y*=(1.f/16384.f); float2 z1=Zs[t];
;               float o0=x0*(y.x+z1.x*bias1)*bf2f(rz[t]); float o1=x1*(y.y+z1.y*bias1)*bf2f(rz[8192+t]);
;               ybT[(size_t)c*16384+t]=f2bf(o0); ybT[(size_t)c*16384+8192+t]=f2bf(o1); } }
	v_pk_mul_f32 v[222:223], v[58:59], v[10:11] op_sel:[1,1] op_sel_hi:[1,0]
	v_pk_fma_f32 v[22:23], v[58:59], v[10:11], v[222:223] op_sel:[0,0,0] op_sel_hi:[0,1,1] neg_lo:[0,0,1]
	v_pk_mul_f32 v[222:223], v[22:23], v[22:23] op_sel:[1,1] op_sel_hi:[1,0]
	v_pk_fma_f32 v[24:25], v[22:23], v[22:23], v[222:223] op_sel:[0,0,0] op_sel_hi:[0,1,1] neg_lo:[0,0,1]
	v_pk_mul_f32 v[222:223], v[24:25], v[22:23] op_sel:[1,1] op_sel_hi:[1,0]
	v_pk_fma_f32 v[26:27], v[24:25], v[22:23], v[222:223] op_sel:[0,0,0] op_sel_hi:[0,1,1] neg_lo:[0,0,1]
	v_pk_mul_f32 v[222:223], v[62:63], v[22:23] op_sel:[1,1] op_sel_hi:[0,1]
	v_pk_fma_f32 v[28:29], v[62:63], v[22:23], v[222:223] op_sel:[0,0,0] op_sel_hi:[1,0,1] neg_hi:[0,0,1]
	v_pk_mul_f32 v[222:223], v[64:65], v[24:25] op_sel:[1,1] op_sel_hi:[0,1]
	v_pk_fma_f32 v[30:31], v[64:65], v[24:25], v[222:223] op_sel:[0,0,0] op_sel_hi:[1,0,1] neg_hi:[0,0,1]
	v_pk_mul_f32 v[222:223], v[66:67], v[26:27] op_sel:[1,1] op_sel_hi:[0,1]
	v_pk_fma_f32 v[68:69], v[66:67], v[26:27], v[222:223] op_sel:[0,0,0] op_sel_hi:[1,0,1] neg_hi:[0,0,1]
	v_pk_add_f32 v[70:71], v[60:61], v[30:31]
	v_pk_add_f32 v[72:73], v[60:61], v[30:31] neg_lo:[0,1] neg_hi:[0,1]
	v_pk_add_f32 v[74:75], v[28:29], v[68:69]
	v_pk_add_f32 v[80:81], v[28:29], v[68:69] neg_lo:[0,1] neg_hi:[0,1]
	v_pk_add_f32 v[82:83], v[70:71], v[74:75]
	v_pk_add_f32 v[84:85], v[72:73], v[80:81] op_sel:[0,1] op_sel_hi:[1,0] neg_lo:[0,1]
	s_waitcnt vmcnt(14)
	v_pk_mul_f32 v[226:227], v[240:241], v[88:89] op_sel_hi:[1,0]
	v_fmac_f32_dpp v226, v240, v87 wave_shr:1 row_mask:0xf bank_mask:0xf
	v_fmac_f32_dpp v227, v241, v87 wave_shr:1 row_mask:0xf bank_mask:0xf
	v_fmac_f32_dpp v226, v240, v89 wave_shl:1 row_mask:0xf bank_mask:0xf
	v_fmac_f32_dpp v227, v241, v89 wave_shl:1 row_mask:0xf bank_mask:0xf
	v_pk_add_f32 v[150:151], v[226:227], v[90:91] op_sel_hi:[1,0]
	v_pk_mul_f32 v[226:227], v[242:243], v[88:89] op_sel_hi:[1,0]
	v_fmac_f32_dpp v226, v242, v87 wave_shr:1 row_mask:0xf bank_mask:0xf
	v_fmac_f32_dpp v227, v243, v87 wave_shr:1 row_mask:0xf bank_mask:0xf
	v_fmac_f32_dpp v226, v242, v89 wave_shl:1 row_mask:0xf bank_mask:0xf
	v_fmac_f32_dpp v227, v243, v89 wave_shl:1 row_mask:0xf bank_mask:0xf
	v_pk_add_f32 v[152:153], v[226:227], v[90:91] op_sel_hi:[1,0]
	v_pk_mul_f32 v[158:159], v[248:249], v[90:91] op_sel:[0,1] op_sel_hi:[1,1]
	v_pk_fma_f32 v[158:159], v[82:83], v[160:161], v[158:159]
	v_pk_mul_f32 v[158:159], v[150:151], v[158:159]
	v_pk_mul_f32 v[158:159], v[158:159], v[244:245]
	v_cvt_pk_bf16_f32 v224, v158, v159
	global_store_short v[110:111], v224, off offset:1024
	global_store_short_d16_hi v[118:119], v224, off offset:1024
	v_pk_mul_f32 v[158:159], v[250:251], v[90:91] op_sel:[0,1] op_sel_hi:[1,1]
	v_pk_fma_f32 v[158:159], v[84:85], v[160:161], v[158:159]
	v_pk_mul_f32 v[158:159], v[152:153], v[158:159]
	v_pk_mul_f32 v[158:159], v[158:159], v[246:247]
	v_cvt_pk_bf16_f32 v224, v158, v159
	global_store_short v[114:115], v224, off offset:1024
	global_store_short_d16_hi v[122:123], v224, off offset:1024
	global_load_short_d16_hi v240, v0, s[96:97] offset:3072
	global_load_short_d16_hi v241, v0, s[74:75] offset:3072
	global_load_short_d16_hi v244, v0, s[72:73] offset:3072
	global_load_short_d16_hi v245, v0, s[12:13] offset:3072
	global_load_short_d16_hi v242, v2, s[96:97] offset:3072
	global_load_short_d16_hi v243, v2, s[74:75] offset:3072
	global_load_short_d16_hi v246, v2, s[72:73] offset:3072
	global_load_short_d16_hi v247, v2, s[12:13] offset:3072
	v_add_u32_e32 v6, 0x3000, v5
	global_load_dwordx2 v[248:249], v6, s[80:81] sc1
	global_load_dwordx2 v[250:251], v6, s[50:51] sc1
	ds_read_b64 v[58:59], v7 offset:192
	ds_read_b64 v[60:61], v8 offset:12288
	ds_read_b64 v[62:63], v8 offset:45056
	ds_read_b64 v[64:65], v9 offset:12288
	ds_read_b64 v[66:67], v9 offset:45056
	s_waitcnt lgkmcnt(5)
	v_pk_mul_f32 v[222:223], v[12:13], v[10:11] op_sel:[1,1] op_sel_hi:[1,0]
	v_pk_fma_f32 v[22:23], v[12:13], v[10:11], v[222:223] op_sel:[0,0,0] op_sel_hi:[0,1,1] neg_lo:[0,0,1]
	v_pk_mul_f32 v[222:223], v[22:23], v[22:23] op_sel:[1,1] op_sel_hi:[1,0]
	v_pk_fma_f32 v[24:25], v[22:23], v[22:23], v[222:223] op_sel:[0,0,0] op_sel_hi:[0,1,1] neg_lo:[0,0,1]
	v_pk_mul_f32 v[222:223], v[24:25], v[22:23] op_sel:[1,1] op_sel_hi:[1,0]
	v_pk_fma_f32 v[26:27], v[24:25], v[22:23], v[222:223] op_sel:[0,0,0] op_sel_hi:[0,1,1] neg_lo:[0,0,1]
	v_pk_mul_f32 v[222:223], v[16:17], v[22:23] op_sel:[1,1] op_sel_hi:[0,1]
	v_pk_fma_f32 v[28:29], v[16:17], v[22:23], v[222:223] op_sel:[0,0,0] op_sel_hi:[1,0,1] neg_hi:[0,0,1]
	v_pk_mul_f32 v[222:223], v[18:19], v[24:25] op_sel:[1,1] op_sel_hi:[0,1]
	v_pk_fma_f32 v[30:31], v[18:19], v[24:25], v[222:223] op_sel:[0,0,0] op_sel_hi:[1,0,1] neg_hi:[0,0,1]
	v_pk_mul_f32 v[222:223], v[20:21], v[26:27] op_sel:[1,1] op_sel_hi:[0,1]
	v_pk_fma_f32 v[68:69], v[20:21], v[26:27], v[222:223] op_sel:[0,0,0] op_sel_hi:[1,0,1] neg_hi:[0,0,1]
	v_pk_add_f32 v[70:71], v[14:15], v[30:31]
	v_pk_add_f32 v[72:73], v[14:15], v[30:31] neg_lo:[0,1] neg_hi:[0,1]
	v_pk_add_f32 v[74:75], v[28:29], v[68:69]
	v_pk_add_f32 v[80:81], v[28:29], v[68:69] neg_lo:[0,1] neg_hi:[0,1]
	v_pk_add_f32 v[82:83], v[70:71], v[74:75]
	v_pk_add_f32 v[84:85], v[72:73], v[80:81] op_sel:[0,1] op_sel_hi:[1,0] neg_lo:[0,1]
	s_waitcnt vmcnt(14)
; __device__ __forceinline__ float bf2f(u16 h){ return __uint_as_float(((unsigned)h)<<16); }
; HD float2 cmul(float2 a, float2 b){ return make_float2(a.x*b.x - a.y*b.y, a.x*b.y + a.y*b.x); }
; HD float2 cmulc(float2 a, float2 b){ return make_float2(a.x*b.x + a.y*b.y, a.y*b.x - a.x*b.y); }
; HD void inv12_half(const float2* Z, const float2* twA, const float2* twB, int t, float2& x0, float2& x1){
;   float2 w1=cmul(twA[t>>6],twB[t&63]), w2=cmul(w1,w1), w3=cmul(w2,w1);
;   float2 b0=Z[t], b1=cmulc(Z[t+4096],w1), b2=cmulc(Z[t+8192],w2), b3=cmulc(Z[t+12288],w3);
;   float2 s02=make_float2(b0.x+b2.x,b0.y+b2.y), d02=make_float2(b0.x-b2.x,b0.y-b2.y);
;   float2 s13=make_float2(b1.x+b3.x,b1.y+b3.y), d13=make_float2(b1.x-b3.x,b1.y-b3.y);
;   x0=make_float2(s02.x+s13.x,s02.y+s13.y);
;   x1=make_float2(d02.x-d13.y,d02.y+d13.x);
; }
; __device__ __forceinline__ void phase_hyena(KP kp_, int hf){ asm volatile("" : "+s"(kp_)); const Params p=load_params(kp_);
;     ...
;         } else { int tq=tid; asm volatile("" : "+v"(tq));
;           _Pragma("unroll 4") for (int i=0;i<8;++i){ int tb=tq+512*i; float2 xr[2]; inv12_half(Z,twA,twB,tb,xr[0],xr[1]);
;             _Pragma("unroll") for (int hh=0;hh<2;++hh){ int t=tb+hh*4096;
;               float x0=hconv3(r2,t,wb0,wb1,wb2,bb_), x1=hconv3(r2+8192,t,wb0,wb1,wb2,bb_);
;               float2 y=xr[hh]; y.x*=(1.f/16384.f); y.y*=(1.f/16384.f); float2 z1=Zs[t];
;               float o0=x0*(y.x+z1.x*bias1)*bf2f(rz[t]); float o1=x1*(y.y+z1.y*bias1)*bf2f(rz[8192+t]);
;               ybT[(size_t)c*16384+t]=f2bf(o0); ybT[(size_t)c*16384+8192+t]=f2bf(o1); } }
	v_pk_mul_f32 v[226:227], v[228:229], v[88:89] op_sel_hi:[1,0]
	v_fmac_f32_dpp v226, v228, v87 wave_shr:1 row_mask:0xf bank_mask:0xf
	v_fmac_f32_dpp v227, v229, v87 wave_shr:1 row_mask:0xf bank_mask:0xf
	v_fmac_f32_dpp v226, v228, v89 wave_shl:1 row_mask:0xf bank_mask:0xf
	v_fmac_f32_dpp v227, v229, v89 wave_shl:1 row_mask:0xf bank_mask:0xf
	v_pk_add_f32 v[150:151], v[226:227], v[90:91] op_sel_hi:[1,0]
	v_pk_mul_f32 v[226:227], v[230:231], v[88:89] op_sel_hi:[1,0]
	v_fmac_f32_dpp v226, v230, v87 wave_shr:1 row_mask:0xf bank_mask:0xf
	v_fmac_f32_dpp v227, v231, v87 wave_shr:1 row_mask:0xf bank_mask:0xf
	v_fmac_f32_dpp v226, v230, v89 wave_shl:1 row_mask:0xf bank_mask:0xf
	v_fmac_f32_dpp v227, v231, v89 wave_shl:1 row_mask:0xf bank_mask:0xf
	v_pk_add_f32 v[152:153], v[226:227], v[90:91] op_sel_hi:[1,0]
	v_pk_mul_f32 v[158:159], v[236:237], v[90:91] op_sel:[0,1] op_sel_hi:[1,1]
	v_pk_fma_f32 v[158:159], v[82:83], v[160:161], v[158:159]
	v_pk_mul_f32 v[158:159], v[150:151], v[158:159]
	v_pk_mul_f32 v[158:159], v[158:159], v[232:233]
	v_cvt_pk_bf16_f32 v224, v158, v159
	global_store_short v[110:111], v224, off offset:2048
	global_store_short_d16_hi v[118:119], v224, off offset:2048
	v_pk_mul_f32 v[158:159], v[238:239], v[90:91] op_sel:[0,1] op_sel_hi:[1,1]
	v_pk_fma_f32 v[158:159], v[84:85], v[160:161], v[158:159]
	v_pk_mul_f32 v[158:159], v[152:153], v[158:159]
	v_pk_mul_f32 v[158:159], v[158:159], v[234:235]
	v_cvt_pk_bf16_f32 v224, v158, v159
	global_store_short v[114:115], v224, off offset:2048
	global_store_short_d16_hi v[122:123], v224, off offset:2048
	global_load_short_d16_hi v228, v1, s[96:97] offset:0
	global_load_short_d16_hi v229, v1, s[74:75] offset:0
	global_load_short_d16_hi v232, v1, s[72:73] offset:0
	global_load_short_d16_hi v233, v1, s[12:13] offset:0
	global_load_short_d16_hi v230, v4, s[96:97] offset:0
	global_load_short_d16_hi v231, v4, s[74:75] offset:0
	global_load_short_d16_hi v234, v4, s[72:73] offset:0
	global_load_short_d16_hi v235, v4, s[12:13] offset:0
	v_add_u32_e32 v6, 0x4000, v5
	global_load_dwordx2 v[236:237], v6, s[80:81] sc1
	global_load_dwordx2 v[238:239], v6, s[50:51] sc1
	ds_read_b64 v[12:13], v7 offset:256
	ds_read_b64 v[14:15], v8 offset:16384
	ds_read_b64 v[16:17], v8 offset:49152
	ds_read_b64 v[18:19], v9 offset:16384
	ds_read_b64 v[20:21], v9 offset:49152
	s_waitcnt lgkmcnt(5)
	v_pk_mul_f32 v[222:223], v[58:59], v[10:11] op_sel:[1,1] op_sel_hi:[1,0]
	v_pk_fma_f32 v[22:23], v[58:59], v[10:11], v[222:223] op_sel:[0,0,0] op_sel_hi:[0,1,1] neg_lo:[0,0,1]
	v_pk_mul_f32 v[222:223], v[22:23], v[22:23] op_sel:[1,1] op_sel_hi:[1,0]
	v_pk_fma_f32 v[24:25], v[22:23], v[22:23], v[222:223] op_sel:[0,0,0] op_sel_hi:[0,1,1] neg_lo:[0,0,1]
	v_pk_mul_f32 v[222:223], v[24:25], v[22:23] op_sel:[1,1] op_sel_hi:[1,0]
	v_pk_fma_f32 v[26:27], v[24:25], v[22:23], v[222:223] op_sel:[0,0,0] op_sel_hi:[0,1,1] neg_lo:[0,0,1]
	v_pk_mul_f32 v[222:223], v[62:63], v[22:23] op_sel:[1,1] op_sel_hi:[0,1]
	v_pk_fma_f32 v[28:29], v[62:63], v[22:23], v[222:223] op_sel:[0,0,0] op_sel_hi:[1,0,1] neg_hi:[0,0,1]
	v_pk_mul_f32 v[222:223], v[64:65], v[24:25] op_sel:[1,1] op_sel_hi:[0,1]
	v_pk_fma_f32 v[30:31], v[64:65], v[24:25], v[222:223] op_sel:[0,0,0] op_sel_hi:[1,0,1] neg_hi:[0,0,1]
	v_pk_mul_f32 v[222:223], v[66:67], v[26:27] op_sel:[1,1] op_sel_hi:[0,1]
	v_pk_fma_f32 v[68:69], v[66:67], v[26:27], v[222:223] op_sel:[0,0,0] op_sel_hi:[1,0,1] neg_hi:[0,0,1]
	v_pk_add_f32 v[70:71], v[60:61], v[30:31]
	v_pk_add_f32 v[72:73], v[60:61], v[30:31] neg_lo:[0,1] neg_hi:[0,1]
	v_pk_add_f32 v[74:75], v[28:29], v[68:69]
	v_pk_add_f32 v[80:81], v[28:29], v[68:69] neg_lo:[0,1] neg_hi:[0,1]
	v_pk_add_f32 v[82:83], v[70:71], v[74:75]
	v_pk_add_f32 v[84:85], v[72:73], v[80:81] op_sel:[0,1] op_sel_hi:[1,0] neg_lo:[0,1]
	s_waitcnt vmcnt(14)
	v_pk_mul_f32 v[226:227], v[240:241], v[88:89] op_sel_hi:[1,0]
	v_fmac_f32_dpp v226, v240, v87 wave_shr:1 row_mask:0xf bank_mask:0xf
	v_fmac_f32_dpp v227, v241, v87 wave_shr:1 row_mask:0xf bank_mask:0xf
	v_fmac_f32_dpp v226, v240, v89 wave_shl:1 row_mask:0xf bank_mask:0xf
	v_fmac_f32_dpp v227, v241, v89 wave_shl:1 row_mask:0xf bank_mask:0xf
	v_pk_add_f32 v[150:151], v[226:227], v[90:91] op_sel_hi:[1,0]
	v_pk_mul_f32 v[226:227], v[242:243], v[88:89] op_sel_hi:[1,0]
	v_fmac_f32_dpp v226, v242, v87 wave_shr:1 row_mask:0xf bank_mask:0xf
	v_fmac_f32_dpp v227, v243, v87 wave_shr:1 row_mask:0xf bank_mask:0xf
	v_fmac_f32_dpp v226, v242, v89 wave_shl:1 row_mask:0xf bank_mask:0xf
	v_fmac_f32_dpp v227, v243, v89 wave_shl:1 row_mask:0xf bank_mask:0xf
	v_pk_add_f32 v[152:153], v[226:227], v[90:91] op_sel_hi:[1,0]
	v_pk_mul_f32 v[158:159], v[248:249], v[90:91] op_sel:[0,1] op_sel_hi:[1,1]
	v_pk_fma_f32 v[158:159], v[82:83], v[160:161], v[158:159]
	v_pk_mul_f32 v[158:159], v[150:151], v[158:159]
	v_pk_mul_f32 v[158:159], v[158:159], v[244:245]
	v_cvt_pk_bf16_f32 v224, v158, v159
	global_store_short v[110:111], v224, off offset:3072
	global_store_short_d16_hi v[118:119], v224, off offset:3072
	v_pk_mul_f32 v[158:159], v[250:251], v[90:91] op_sel:[0,1] op_sel_hi:[1,1]
	v_pk_fma_f32 v[158:159], v[84:85], v[160:161], v[158:159]
	v_pk_mul_f32 v[158:159], v[152:153], v[158:159]
	v_pk_mul_f32 v[158:159], v[158:159], v[246:247]
	v_cvt_pk_bf16_f32 v224, v158, v159
	global_store_short v[114:115], v224, off offset:3072
	global_store_short_d16_hi v[122:123], v224, off offset:3072
	global_load_short_d16_hi v240, v1, s[96:97] offset:1024
	global_load_short_d16_hi v241, v1, s[74:75] offset:1024
	global_load_short_d16_hi v244, v1, s[72:73] offset:1024
	global_load_short_d16_hi v245, v1, s[12:13] offset:1024
	global_load_short_d16_hi v242, v4, s[96:97] offset:1024
	global_load_short_d16_hi v243, v4, s[74:75] offset:1024
	global_load_short_d16_hi v246, v4, s[72:73] offset:1024
	global_load_short_d16_hi v247, v4, s[12:13] offset:1024
	v_add_u32_e32 v6, 0x5000, v5
	global_load_dwordx2 v[248:249], v6, s[80:81] sc1
	global_load_dwordx2 v[250:251], v6, s[50:51] sc1
	ds_read_b64 v[58:59], v7 offset:320
	ds_read_b64 v[60:61], v8 offset:20480
	ds_read_b64 v[62:63], v8 offset:53248
	ds_read_b64 v[64:65], v9 offset:20480
	ds_read_b64 v[66:67], v9 offset:53248
	s_waitcnt lgkmcnt(5)
; __device__ __forceinline__ float bf2f(u16 h){ return __uint_as_float(((unsigned)h)<<16); }
; HD float2 cmul(float2 a, float2 b){ return make_float2(a.x*b.x - a.y*b.y, a.x*b.y + a.y*b.x); }
; HD float2 cmulc(float2 a, float2 b){ return make_float2(a.x*b.x + a.y*b.y, a.y*b.x - a.x*b.y); }
; HD void inv12_half(const float2* Z, const float2* twA, const float2* twB, int t, float2& x0, float2& x1){
;   float2 w1=cmul(twA[t>>6],twB[t&63]), w2=cmul(w1,w1), w3=cmul(w2,w1);
;   float2 b0=Z[t], b1=cmulc(Z[t+4096],w1), b2=cmulc(Z[t+8192],w2), b3=cmulc(Z[t+12288],w3);
;   float2 s02=make_float2(b0.x+b2.x,b0.y+b2.y), d02=make_float2(b0.x-b2.x,b0.y-b2.y);
;   float2 s13=make_float2(b1.x+b3.x,b1.y+b3.y), d13=make_float2(b1.x-b3.x,b1.y-b3.y);
;   x0=make_float2(s02.x+s13.x,s02.y+s13.y);
;   x1=make_float2(d02.x-d13.y,d02.y+d13.x);
; }
; __device__ __forceinline__ void phase_hyena(KP kp_, int hf){ asm volatile("" : "+s"(kp_)); const Params p=load_params(kp_);
;     ...
;         } else { int tq=tid; asm volatile("" : "+v"(tq));
;           _Pragma("unroll 4") for (int i=0;i<8;++i){ int tb=tq+512*i; float2 xr[2]; inv12_half(Z,twA,twB,tb,xr[0],xr[1]);
;             _Pragma("unroll") for (int hh=0;hh<2;++hh){ int t=tb+hh*4096;
;               float x0=hconv3(r2,t,wb0,wb1,wb2,bb_), x1=hconv3(r2+8192,t,wb0,wb1,wb2,bb_);
;               float2 y=xr[hh]; y.x*=(1.f/16384.f); y.y*=(1.f/16384.f); float2 z1=Zs[t];
;               float o0=x0*(y.x+z1.x*bias1)*bf2f(rz[t]); float o1=x1*(y.y+z1.y*bias1)*bf2f(rz[8192+t]);
;               ybT[(size_t)c*16384+t]=f2bf(o0); ybT[(size_t)c*16384+8192+t]=f2bf(o1); } }
	v_pk_mul_f32 v[222:223], v[12:13], v[10:11] op_sel:[1,1] op_sel_hi:[1,0]
	v_pk_fma_f32 v[22:23], v[12:13], v[10:11], v[222:223] op_sel:[0,0,0] op_sel_hi:[0,1,1] neg_lo:[0,0,1]
	v_pk_mul_f32 v[222:223], v[22:23], v[22:23] op_sel:[1,1] op_sel_hi:[1,0]
	v_pk_fma_f32 v[24:25], v[22:23], v[22:23], v[222:223] op_sel:[0,0,0] op_sel_hi:[0,1,1] neg_lo:[0,0,1]
	v_pk_mul_f32 v[222:223], v[24:25], v[22:23] op_sel:[1,1] op_sel_hi:[1,0]
	v_pk_fma_f32 v[26:27], v[24:25], v[22:23], v[222:223] op_sel:[0,0,0] op_sel_hi:[0,1,1] neg_lo:[0,0,1]
	v_pk_mul_f32 v[222:223], v[16:17], v[22:23] op_sel:[1,1] op_sel_hi:[0,1]
	v_pk_fma_f32 v[28:29], v[16:17], v[22:23], v[222:223] op_sel:[0,0,0] op_sel_hi:[1,0,1] neg_hi:[0,0,1]
	v_pk_mul_f32 v[222:223], v[18:19], v[24:25] op_sel:[1,1] op_sel_hi:[0,1]
	v_pk_fma_f32 v[30:31], v[18:19], v[24:25], v[222:223] op_sel:[0,0,0] op_sel_hi:[1,0,1] neg_hi:[0,0,1]
	v_pk_mul_f32 v[222:223], v[20:21], v[26:27] op_sel:[1,1] op_sel_hi:[0,1]
	v_pk_fma_f32 v[68:69], v[20:21], v[26:27], v[222:223] op_sel:[0,0,0] op_sel_hi:[1,0,1] neg_hi:[0,0,1]
	v_pk_add_f32 v[70:71], v[14:15], v[30:31]
	v_pk_add_f32 v[72:73], v[14:15], v[30:31] neg_lo:[0,1] neg_hi:[0,1]
	v_pk_add_f32 v[74:75], v[28:29], v[68:69]
	v_pk_add_f32 v[80:81], v[28:29], v[68:69] neg_lo:[0,1] neg_hi:[0,1]
	v_pk_add_f32 v[82:83], v[70:71], v[74:75]
	v_pk_add_f32 v[84:85], v[72:73], v[80:81] op_sel:[0,1] op_sel_hi:[1,0] neg_lo:[0,1]
	s_waitcnt vmcnt(14)
	v_pk_mul_f32 v[226:227], v[228:229], v[88:89] op_sel_hi:[1,0]
	v_fmac_f32_dpp v226, v228, v87 wave_shr:1 row_mask:0xf bank_mask:0xf
	v_fmac_f32_dpp v227, v229, v87 wave_shr:1 row_mask:0xf bank_mask:0xf
	v_fmac_f32_dpp v226, v228, v89 wave_shl:1 row_mask:0xf bank_mask:0xf
	v_fmac_f32_dpp v227, v229, v89 wave_shl:1 row_mask:0xf bank_mask:0xf
	v_pk_add_f32 v[150:151], v[226:227], v[90:91] op_sel_hi:[1,0]
	v_pk_mul_f32 v[226:227], v[230:231], v[88:89] op_sel_hi:[1,0]
	v_fmac_f32_dpp v226, v230, v87 wave_shr:1 row_mask:0xf bank_mask:0xf
	v_fmac_f32_dpp v227, v231, v87 wave_shr:1 row_mask:0xf bank_mask:0xf
	v_fmac_f32_dpp v226, v230, v89 wave_shl:1 row_mask:0xf bank_mask:0xf
	v_fmac_f32_dpp v227, v231, v89 wave_shl:1 row_mask:0xf bank_mask:0xf
	v_pk_add_f32 v[152:153], v[226:227], v[90:91] op_sel_hi:[1,0]
	v_pk_mul_f32 v[158:159], v[236:237], v[90:91] op_sel:[0,1] op_sel_hi:[1,1]
	v_pk_fma_f32 v[158:159], v[82:83], v[160:161], v[158:159]
	v_pk_mul_f32 v[158:159], v[150:151], v[158:159]
	v_pk_mul_f32 v[158:159], v[158:159], v[232:233]
	v_cvt_pk_bf16_f32 v224, v158, v159
	global_store_short v[112:113], v224, off offset:0
	global_store_short_d16_hi v[120:121], v224, off offset:0
	v_pk_mul_f32 v[158:159], v[238:239], v[90:91] op_sel:[0,1] op_sel_hi:[1,1]
	v_pk_fma_f32 v[158:159], v[84:85], v[160:161], v[158:159]
	v_pk_mul_f32 v[158:159], v[152:153], v[158:159]
	v_pk_mul_f32 v[158:159], v[158:159], v[234:235]
	v_cvt_pk_bf16_f32 v224, v158, v159
	global_store_short v[116:117], v224, off offset:0
	global_store_short_d16_hi v[124:125], v224, off offset:0
	global_load_short_d16_hi v228, v1, s[96:97] offset:2048
	global_load_short_d16_hi v229, v1, s[74:75] offset:2048
	global_load_short_d16_hi v232, v1, s[72:73] offset:2048
	global_load_short_d16_hi v233, v1, s[12:13] offset:2048
	global_load_short_d16_hi v230, v4, s[96:97] offset:2048
	global_load_short_d16_hi v231, v4, s[74:75] offset:2048
	global_load_short_d16_hi v234, v4, s[72:73] offset:2048
	global_load_short_d16_hi v235, v4, s[12:13] offset:2048
	v_add_u32_e32 v6, 0x6000, v5
	global_load_dwordx2 v[236:237], v6, s[80:81] sc1
	global_load_dwordx2 v[238:239], v6, s[50:51] sc1
	ds_read_b64 v[12:13], v7 offset:384
	ds_read_b64 v[14:15], v8 offset:24576
	ds_read_b64 v[16:17], v8 offset:57344
	ds_read_b64 v[18:19], v9 offset:24576
	ds_read_b64 v[20:21], v9 offset:57344
	s_waitcnt lgkmcnt(5)
	v_pk_mul_f32 v[222:223], v[58:59], v[10:11] op_sel:[1,1] op_sel_hi:[1,0]
	v_pk_fma_f32 v[22:23], v[58:59], v[10:11], v[222:223] op_sel:[0,0,0] op_sel_hi:[0,1,1] neg_lo:[0,0,1]
	v_pk_mul_f32 v[222:223], v[22:23], v[22:23] op_sel:[1,1] op_sel_hi:[1,0]
	v_pk_fma_f32 v[24:25], v[22:23], v[22:23], v[222:223] op_sel:[0,0,0] op_sel_hi:[0,1,1] neg_lo:[0,0,1]
	v_pk_mul_f32 v[222:223], v[24:25], v[22:23] op_sel:[1,1] op_sel_hi:[1,0]
	v_pk_fma_f32 v[26:27], v[24:25], v[22:23], v[222:223] op_sel:[0,0,0] op_sel_hi:[0,1,1] neg_lo:[0,0,1]
	v_pk_mul_f32 v[222:223], v[62:63], v[22:23] op_sel:[1,1] op_sel_hi:[0,1]
	v_pk_fma_f32 v[28:29], v[62:63], v[22:23], v[222:223] op_sel:[0,0,0] op_sel_hi:[1,0,1] neg_hi:[0,0,1]
	v_pk_mul_f32 v[222:223], v[64:65], v[24:25] op_sel:[1,1] op_sel_hi:[0,1]
	v_pk_fma_f32 v[30:31], v[64:65], v[24:25], v[222:223] op_sel:[0,0,0] op_sel_hi:[1,0,1] neg_hi:[0,0,1]
	v_pk_mul_f32 v[222:223], v[66:67], v[26:27] op_sel:[1,1] op_sel_hi:[0,1]
	v_pk_fma_f32 v[68:69], v[66:67], v[26:27], v[222:223] op_sel:[0,0,0] op_sel_hi:[1,0,1] neg_hi:[0,0,1]
	v_pk_add_f32 v[70:71], v[60:61], v[30:31]
	v_pk_add_f32 v[72:73], v[60:61], v[30:31] neg_lo:[0,1] neg_hi:[0,1]
	v_pk_add_f32 v[74:75], v[28:29], v[68:69]
	v_pk_add_f32 v[80:81], v[28:29], v[68:69] neg_lo:[0,1] neg_hi:[0,1]
	v_pk_add_f32 v[82:83], v[70:71], v[74:75]
	v_pk_add_f32 v[84:85], v[72:73], v[80:81] op_sel:[0,1] op_sel_hi:[1,0] neg_lo:[0,1]
	s_waitcnt vmcnt(14)
; __device__ __forceinline__ float bf2f(u16 h){ return __uint_as_float(((unsigned)h)<<16); }
; HD float2 cmul(float2 a, float2 b){ return make_float2(a.x*b.x - a.y*b.y, a.x*b.y + a.y*b.x); }
; HD float2 cmulc(float2 a, float2 b){ return make_float2(a.x*b.x + a.y*b.y, a.y*b.x - a.x*b.y); }
; HD void inv12_half(const float2* Z, const float2* twA, const float2* twB, int t, float2& x0, float2& x1){
;   float2 w1=cmul(twA[t>>6],twB[t&63]), w2=cmul(w1,w1), w3=cmul(w2,w1);
;   float2 b0=Z[t], b1=cmulc(Z[t+4096],w1), b2=cmulc(Z[t+8192],w2), b3=cmulc(Z[t+12288],w3);
;   float2 s02=make_float2(b0.x+b2.x,b0.y+b2.y), d02=make_float2(b0.x-b2.x,b0.y-b2.y);
;   float2 s13=make_float2(b1.x+b3.x,b1.y+b3.y), d13=make_float2(b1.x-b3.x,b1.y-b3.y);
;   x0=make_float2(s02.x+s13.x,s02.y+s13.y);
;   x1=make_float2(d02.x-d13.y,d02.y+d13.x);
; }
; __device__ __forceinline__ void phase_hyena(KP kp_, int hf){ asm volatile("" : "+s"(kp_)); const Params p=load_params(kp_);
;     ...
;         } else { int tq=tid; asm volatile("" : "+v"(tq));
;           _Pragma("unroll 4") for (int i=0;i<8;++i){ int tb=tq+512*i; float2 xr[2]; inv12_half(Z,twA,twB,tb,xr[0],xr[1]);
;             _Pragma("unroll") for (int hh=0;hh<2;++hh){ int t=tb+hh*4096;
;               float x0=hconv3(r2,t,wb0,wb1,wb2,bb_), x1=hconv3(r2+8192,t,wb0,wb1,wb2,bb_);
;               float2 y=xr[hh]; y.x*=(1.f/16384.f); y.y*=(1.f/16384.f); float2 z1=Zs[t];
;               float o0=x0*(y.x+z1.x*bias1)*bf2f(rz[t]); float o1=x1*(y.y+z1.y*bias1)*bf2f(rz[8192+t]);
;               ybT[(size_t)c*16384+t]=f2bf(o0); ybT[(size_t)c*16384+8192+t]=f2bf(o1); } }
	v_pk_mul_f32 v[226:227], v[240:241], v[88:89] op_sel_hi:[1,0]
	v_fmac_f32_dpp v226, v240, v87 wave_shr:1 row_mask:0xf bank_mask:0xf
	v_fmac_f32_dpp v227, v241, v87 wave_shr:1 row_mask:0xf bank_mask:0xf
	v_fmac_f32_dpp v226, v240, v89 wave_shl:1 row_mask:0xf bank_mask:0xf
	v_fmac_f32_dpp v227, v241, v89 wave_shl:1 row_mask:0xf bank_mask:0xf
	v_pk_add_f32 v[150:151], v[226:227], v[90:91] op_sel_hi:[1,0]
	v_pk_mul_f32 v[226:227], v[242:243], v[88:89] op_sel_hi:[1,0]
	v_fmac_f32_dpp v226, v242, v87 wave_shr:1 row_mask:0xf bank_mask:0xf
	v_fmac_f32_dpp v227, v243, v87 wave_shr:1 row_mask:0xf bank_mask:0xf
	v_fmac_f32_dpp v226, v242, v89 wave_shl:1 row_mask:0xf bank_mask:0xf
	v_fmac_f32_dpp v227, v243, v89 wave_shl:1 row_mask:0xf bank_mask:0xf
	v_pk_add_f32 v[152:153], v[226:227], v[90:91] op_sel_hi:[1,0]
	v_pk_mul_f32 v[158:159], v[248:249], v[90:91] op_sel:[0,1] op_sel_hi:[1,1]
	v_pk_fma_f32 v[158:159], v[82:83], v[160:161], v[158:159]
	v_pk_mul_f32 v[158:159], v[150:151], v[158:159]
	v_pk_mul_f32 v[158:159], v[158:159], v[244:245]
	v_cvt_pk_bf16_f32 v224, v158, v159
	global_store_short v[112:113], v224, off offset:1024
	global_store_short_d16_hi v[120:121], v224, off offset:1024
	v_pk_mul_f32 v[158:159], v[250:251], v[90:91] op_sel:[0,1] op_sel_hi:[1,1]
	v_pk_fma_f32 v[158:159], v[84:85], v[160:161], v[158:159]
	v_pk_mul_f32 v[158:159], v[152:153], v[158:159]
	v_pk_mul_f32 v[158:159], v[158:159], v[246:247]
	v_cvt_pk_bf16_f32 v224, v158, v159
	global_store_short v[116:117], v224, off offset:1024
	global_store_short_d16_hi v[124:125], v224, off offset:1024
	global_load_short_d16_hi v240, v1, s[96:97] offset:3072
	global_load_short_d16_hi v241, v1, s[74:75] offset:3072
	global_load_short_d16_hi v244, v1, s[72:73] offset:3072
	global_load_short_d16_hi v245, v1, s[12:13] offset:3072
	global_load_short_d16_hi v242, v4, s[96:97] offset:3072
	global_load_short_d16_hi v243, v4, s[74:75] offset:3072
	global_load_short_d16_hi v246, v4, s[72:73] offset:3072
	global_load_short_d16_hi v247, v4, s[12:13] offset:3072
	v_add_u32_e32 v6, 0x7000, v5
	global_load_dwordx2 v[248:249], v6, s[80:81] sc1
	global_load_dwordx2 v[250:251], v6, s[50:51] sc1
	ds_read_b64 v[58:59], v7 offset:448
	ds_read_b64 v[60:61], v8 offset:28672
	ds_read_b64 v[62:63], v8 offset:61440
	ds_read_b64 v[64:65], v9 offset:28672
	ds_read_b64 v[66:67], v9 offset:61440
	s_waitcnt lgkmcnt(5)
	v_pk_mul_f32 v[222:223], v[12:13], v[10:11] op_sel:[1,1] op_sel_hi:[1,0]
	v_pk_fma_f32 v[22:23], v[12:13], v[10:11], v[222:223] op_sel:[0,0,0] op_sel_hi:[0,1,1] neg_lo:[0,0,1]
	v_pk_mul_f32 v[222:223], v[22:23], v[22:23] op_sel:[1,1] op_sel_hi:[1,0]
	v_pk_fma_f32 v[24:25], v[22:23], v[22:23], v[222:223] op_sel:[0,0,0] op_sel_hi:[0,1,1] neg_lo:[0,0,1]
	v_pk_mul_f32 v[222:223], v[24:25], v[22:23] op_sel:[1,1] op_sel_hi:[1,0]
	v_pk_fma_f32 v[26:27], v[24:25], v[22:23], v[222:223] op_sel:[0,0,0] op_sel_hi:[0,1,1] neg_lo:[0,0,1]
	v_pk_mul_f32 v[222:223], v[16:17], v[22:23] op_sel:[1,1] op_sel_hi:[0,1]
	v_pk_fma_f32 v[28:29], v[16:17], v[22:23], v[222:223] op_sel:[0,0,0] op_sel_hi:[1,0,1] neg_hi:[0,0,1]
	v_pk_mul_f32 v[222:223], v[18:19], v[24:25] op_sel:[1,1] op_sel_hi:[0,1]
	v_pk_fma_f32 v[30:31], v[18:19], v[24:25], v[222:223] op_sel:[0,0,0] op_sel_hi:[1,0,1] neg_hi:[0,0,1]
	v_pk_mul_f32 v[222:223], v[20:21], v[26:27] op_sel:[1,1] op_sel_hi:[0,1]
	v_pk_fma_f32 v[68:69], v[20:21], v[26:27], v[222:223] op_sel:[0,0,0] op_sel_hi:[1,0,1] neg_hi:[0,0,1]
	v_pk_add_f32 v[70:71], v[14:15], v[30:31]
	v_pk_add_f32 v[72:73], v[14:15], v[30:31] neg_lo:[0,1] neg_hi:[0,1]
	v_pk_add_f32 v[74:75], v[28:29], v[68:69]
	v_pk_add_f32 v[80:81], v[28:29], v[68:69] neg_lo:[0,1] neg_hi:[0,1]
	v_pk_add_f32 v[82:83], v[70:71], v[74:75]
	v_pk_add_f32 v[84:85], v[72:73], v[80:81] op_sel:[0,1] op_sel_hi:[1,0] neg_lo:[0,1]
	s_waitcnt vmcnt(14)
; __device__ __forceinline__ float bf2f(u16 h){ return __uint_as_float(((unsigned)h)<<16); }
; __device__ __forceinline__ float hconv3(const u16* __restrict__ row, int t, float w0, float w1, float w2, float bias){
;   float m = bf2f(row[t]);
;   int mi=__float_as_int(m);
;   float l=__int_as_float(__builtin_amdgcn_update_dpp(0, mi, 0x138, 0xf, 0xf, false));
;   float r=__int_as_float(__builtin_amdgcn_update_dpp(0, mi, 0x130, 0xf, 0xf, false));
;   return w0*l+w1*m+w2*r+bias;
; }
; __device__ __forceinline__ void phase_hyena(KP kp_, int hf){ asm volatile("" : "+s"(kp_)); const Params p=load_params(kp_);
;     ...
;           _Pragma("unroll 4") for (int i=0;i<8;++i){ int tb=tq+512*i; float2 xr[2]; inv12_half(Z,twA,twB,tb,xr[0],xr[1]);
;             _Pragma("unroll") for (int hh=0;hh<2;++hh){ int t=tb+hh*4096;
;               float x0=hconv3(r2,t,wb0,wb1,wb2,bb_), x1=hconv3(r2+8192,t,wb0,wb1,wb2,bb_);
;               float2 y=xr[hh]; y.x*=(1.f/16384.f); y.y*=(1.f/16384.f); float2 z1=Zs[t];
;               float o0=x0*(y.x+z1.x*bias1)*bf2f(rz[t]); float o1=x1*(y.y+z1.y*bias1)*bf2f(rz[8192+t]);
;               ybT[(size_t)c*16384+t]=f2bf(o0); ybT[(size_t)c*16384+8192+t]=f2bf(o1); } }
	v_pk_mul_f32 v[226:227], v[228:229], v[88:89] op_sel_hi:[1,0]
	v_fmac_f32_dpp v226, v228, v87 wave_shr:1 row_mask:0xf bank_mask:0xf
	v_fmac_f32_dpp v227, v229, v87 wave_shr:1 row_mask:0xf bank_mask:0xf
	v_fmac_f32_dpp v226, v228, v89 wave_shl:1 row_mask:0xf bank_mask:0xf
	v_fmac_f32_dpp v227, v229, v89 wave_shl:1 row_mask:0xf bank_mask:0xf
	v_pk_add_f32 v[150:151], v[226:227], v[90:91] op_sel_hi:[1,0]
	v_pk_mul_f32 v[226:227], v[230:231], v[88:89] op_sel_hi:[1,0]
	v_fmac_f32_dpp v226, v230, v87 wave_shr:1 row_mask:0xf bank_mask:0xf
	v_fmac_f32_dpp v227, v231, v87 wave_shr:1 row_mask:0xf bank_mask:0xf
	v_fmac_f32_dpp v226, v230, v89 wave_shl:1 row_mask:0xf bank_mask:0xf
	v_fmac_f32_dpp v227, v231, v89 wave_shl:1 row_mask:0xf bank_mask:0xf
	v_pk_add_f32 v[152:153], v[226:227], v[90:91] op_sel_hi:[1,0]
	v_pk_mul_f32 v[158:159], v[236:237], v[90:91] op_sel:[0,1] op_sel_hi:[1,1]
	v_pk_fma_f32 v[158:159], v[82:83], v[160:161], v[158:159]
	v_pk_mul_f32 v[158:159], v[150:151], v[158:159]
	v_pk_mul_f32 v[158:159], v[158:159], v[232:233]
	v_cvt_pk_bf16_f32 v224, v158, v159
	global_store_short v[112:113], v224, off offset:2048
	global_store_short_d16_hi v[120:121], v224, off offset:2048
	v_pk_mul_f32 v[158:159], v[238:239], v[90:91] op_sel:[0,1] op_sel_hi:[1,1]
	v_pk_fma_f32 v[158:159], v[84:85], v[160:161], v[158:159]
	v_pk_mul_f32 v[158:159], v[152:153], v[158:159]
	v_pk_mul_f32 v[158:159], v[158:159], v[234:235]
	v_cvt_pk_bf16_f32 v224, v158, v159
	global_store_short v[116:117], v224, off offset:2048
	global_store_short_d16_hi v[124:125], v224, off offset:2048
	s_waitcnt lgkmcnt(0)
	v_pk_mul_f32 v[222:223], v[58:59], v[10:11] op_sel:[1,1] op_sel_hi:[1,0]
	v_pk_fma_f32 v[22:23], v[58:59], v[10:11], v[222:223] op_sel:[0,0,0] op_sel_hi:[0,1,1] neg_lo:[0,0,1]
	v_pk_mul_f32 v[222:223], v[22:23], v[22:23] op_sel:[1,1] op_sel_hi:[1,0]
	v_pk_fma_f32 v[24:25], v[22:23], v[22:23], v[222:223] op_sel:[0,0,0] op_sel_hi:[0,1,1] neg_lo:[0,0,1]
	v_pk_mul_f32 v[222:223], v[24:25], v[22:23] op_sel:[1,1] op_sel_hi:[1,0]
	v_pk_fma_f32 v[26:27], v[24:25], v[22:23], v[222:223] op_sel:[0,0,0] op_sel_hi:[0,1,1] neg_lo:[0,0,1]
	v_pk_mul_f32 v[222:223], v[62:63], v[22:23] op_sel:[1,1] op_sel_hi:[0,1]
	v_pk_fma_f32 v[28:29], v[62:63], v[22:23], v[222:223] op_sel:[0,0,0] op_sel_hi:[1,0,1] neg_hi:[0,0,1]
	v_pk_mul_f32 v[222:223], v[64:65], v[24:25] op_sel:[1,1] op_sel_hi:[0,1]
	v_pk_fma_f32 v[30:31], v[64:65], v[24:25], v[222:223] op_sel:[0,0,0] op_sel_hi:[1,0,1] neg_hi:[0,0,1]
	v_pk_mul_f32 v[222:223], v[66:67], v[26:27] op_sel:[1,1] op_sel_hi:[0,1]
	v_pk_fma_f32 v[68:69], v[66:67], v[26:27], v[222:223] op_sel:[0,0,0] op_sel_hi:[1,0,1] neg_hi:[0,0,1]
	v_pk_add_f32 v[70:71], v[60:61], v[30:31]
	v_pk_add_f32 v[72:73], v[60:61], v[30:31] neg_lo:[0,1] neg_hi:[0,1]
	v_pk_add_f32 v[74:75], v[28:29], v[68:69]
	v_pk_add_f32 v[80:81], v[28:29], v[68:69] neg_lo:[0,1] neg_hi:[0,1]
	v_pk_add_f32 v[82:83], v[70:71], v[74:75]
	v_pk_add_f32 v[84:85], v[72:73], v[80:81] op_sel:[0,1] op_sel_hi:[1,0] neg_lo:[0,1]
	s_waitcnt vmcnt(4)
	v_pk_mul_f32 v[226:227], v[240:241], v[88:89] op_sel_hi:[1,0]
	v_fmac_f32_dpp v226, v240, v87 wave_shr:1 row_mask:0xf bank_mask:0xf
	v_fmac_f32_dpp v227, v241, v87 wave_shr:1 row_mask:0xf bank_mask:0xf
	v_fmac_f32_dpp v226, v240, v89 wave_shl:1 row_mask:0xf bank_mask:0xf
	v_fmac_f32_dpp v227, v241, v89 wave_shl:1 row_mask:0xf bank_mask:0xf
	v_pk_add_f32 v[150:151], v[226:227], v[90:91] op_sel_hi:[1,0]
	v_pk_mul_f32 v[226:227], v[242:243], v[88:89] op_sel_hi:[1,0]
	v_fmac_f32_dpp v226, v242, v87 wave_shr:1 row_mask:0xf bank_mask:0xf
	v_fmac_f32_dpp v227, v243, v87 wave_shr:1 row_mask:0xf bank_mask:0xf
	v_fmac_f32_dpp v226, v242, v89 wave_shl:1 row_mask:0xf bank_mask:0xf
	v_fmac_f32_dpp v227, v243, v89 wave_shl:1 row_mask:0xf bank_mask:0xf
	v_pk_add_f32 v[152:153], v[226:227], v[90:91] op_sel_hi:[1,0]
	v_pk_mul_f32 v[158:159], v[248:249], v[90:91] op_sel:[0,1] op_sel_hi:[1,1]
	v_pk_fma_f32 v[158:159], v[82:83], v[160:161], v[158:159]
	v_pk_mul_f32 v[158:159], v[150:151], v[158:159]
	v_pk_mul_f32 v[158:159], v[158:159], v[244:245]
	v_cvt_pk_bf16_f32 v224, v158, v159
	global_store_short v[112:113], v224, off offset:3072
	global_store_short_d16_hi v[120:121], v224, off offset:3072
	v_pk_mul_f32 v[158:159], v[250:251], v[90:91] op_sel:[0,1] op_sel_hi:[1,1]
	v_pk_fma_f32 v[158:159], v[84:85], v[160:161], v[158:159]
	v_pk_mul_f32 v[158:159], v[152:153], v[158:159]
	v_pk_mul_f32 v[158:159], v[158:159], v[246:247]
	v_cvt_pk_bf16_f32 v224, v158, v159
	global_store_short v[116:117], v224, off offset:3072
	global_store_short_d16_hi v[124:125], v224, off offset:3072
	s_mov_b32 s50, 0x2000
	s_mov_b32 s51, 0
	s_mov_b64 s[12:13], 0
